# nt cache policy on once-read streaming loads: residual x in the four panel-norm epilogues (first pass) and the x rows of norm1
# speedup vs baseline: 1.0001x; 1.0001x over previous
; __device__ __forceinline__ int fresh_tid() { int t = threadIdx.x; asm volatile("" : "+v"(t)); return t; }
; #define NORM_LOADX(dst, r_) do { const int r__ = (r_); const float* xr_ = r__ < NLAT ? xlat + (size_t)r__ * DM : xctx + (size_t)(r__ - NLAT) * DM; \
;         _Pragma("unroll") for (int j = 0; j < 4; ++j) dst[j] = *(const f32x4*)(xr_ + 4 * lane + 256 * j); } while (0)
; __device__ __forceinline__ void norm_phase(const float* xlat, const float* xctx, const float* gvec, const float* mod, int sh_off, int sc_off, bf16_t* H, int nrows,
;                                            const float* part, const float* pgate, float* xctx_out, int row_lo) {
;     const int tid = fresh_tid(), lane = tid & 63, gw = row_lo + blockIdx.x * 8 + (tid >> 6), NGW = gridDim.x * 8;
;     f32x4 vn[4];
;     ...
;     if (gw < nrows) NORM_LOADX(vn, gw);
;     for (int row = gw; row < nrows; row += NGW) {
;         const int bb = row < NLAT ? row >> 11 : 8;
;         f32x4 v[4]; float ss = 0.f;
; #pragma unroll
;         for (int j = 0; j < 4; ++j) v[j] = vn[j];
;         if (row + NGW < nrows) NORM_LOADX(vn, row + NGW);
;         const float* mp = mod + bb * 6144;
;         f32x4 gg[4], sc[4], sh[4];
; #pragma unroll
;         for (int j = 0; j < 4; ++j) { const int col = 4 * lane + 256 * j; gg[j] = *(const f32x4*)(gvec + col); sc[j] = *(const f32x4*)(mp + sc_off + col); sh[j] = *(const f32x4*)(mp + sh_off + col); }
.LBB0_173:
	s_mul_i32 s0, s72, 0x36000
	v_readlane_b32 s1, v253, 20
	s_add_u32 s48, s1, s0
	v_readlane_b32 s0, v253, 21
	s_addc_u32 s49, s0, 0
	v_readlane_b32 s8, v252, 0
	v_readlane_b32 s52, v252, 16
	v_writelane_b32 v255, s6, 26
	s_and_b64 s[0:1], s[6:7], exec
	v_readlane_b32 s10, v252, 2
	v_readlane_b32 s11, v252, 3
	v_readlane_b32 s53, v252, 17
	v_writelane_b32 v255, s7, 27
	s_cselect_b32 s1, s53, s11
	s_cselect_b32 s0, s52, s10
	v_readlane_b32 s57, v252, 21
	v_writelane_b32 v255, s0, 28
	v_readlane_b32 s56, v252, 20
	v_readlane_b32 s58, v252, 22
	v_writelane_b32 v255, s1, 29
	s_cselect_b32 s0, s57, s27
	v_writelane_b32 v255, s0, 30
	s_cselect_b32 s0, s56, s26
	v_writelane_b32 v255, s0, 31
	v_readlane_b32 s0, v253, 22
	v_readlane_b32 s1, v253, 23
	s_lshl_b32 s58, s72, 10
	s_and_b64 s[6:7], s[0:1], s[4:5]
	s_and_b64 s[0:1], s[6:7], exec
	s_cselect_b32 s0, 0x4000, 0
	v_mov_b32_e32 v19, v192
	v_readlane_b32 s1, v253, 0
	s_add_i32 s1, s0, s1
	v_ashrrev_i32_e32 v18, 6, v19
	v_readlane_b32 s59, v252, 23
	v_add_u32_e32 v16, s1, v18
	s_movk_i32 s1, 0x4800
	v_readlane_b32 s9, v252, 1
	s_mov_b32 s59, s43
	v_cmp_gt_i32_e32 vcc, s1, v16
	v_readlane_b32 s12, v252, 4
	v_readlane_b32 s13, v252, 5
	v_readlane_b32 s14, v252, 6
	v_readlane_b32 s15, v252, 7
	v_readlane_b32 s54, v252, 18
	v_readlane_b32 s55, v252, 19
	v_readlane_b32 s60, v252, 24
	v_readlane_b32 s61, v252, 25
	v_readlane_b32 s62, v252, 26
	v_readlane_b32 s63, v252, 27
	v_readlane_b32 s64, v252, 28
	v_readlane_b32 s65, v252, 29
	v_readlane_b32 s66, v252, 30
	v_readlane_b32 s67, v252, 31
	s_and_saveexec_b64 s[8:9], vcc
	s_cbranch_execz .LBB0_180
	s_movk_i32 s1, 0x4000
	v_readlane_b32 s10, v255, 28
	v_cmp_gt_i32_e32 vcc, s1, v16
	v_readlane_b32 s1, v255, 30
	v_readlane_b32 s11, v255, 29
	v_add_u32_e32 v0, 0xffffc000, v16
	v_ashrrev_i32_e32 v17, 31, v16
	v_mov_b32_e32 v2, s1
	v_mov_b32_e32 v3, s11
	v_readlane_b32 s1, v255, 31
	v_cndmask_b32_e32 v1, 0, v17, vcc
	v_cndmask_b32_e32 v0, v0, v16, vcc
	v_cndmask_b32_e32 v3, v2, v3, vcc
	v_mov_b32_e32 v2, s1
	v_mov_b32_e32 v4, s10
	v_cndmask_b32_e32 v2, v2, v4, vcc
	v_lshlrev_b64 v[0:1], 12, v[0:1]
	v_lshl_add_u64 v[0:1], v[2:3], 0, v[0:1]
	v_lshlrev_b32_e32 v2, 2, v19
	v_and_b32_e32 v80, 0xfc, v2
	v_lshlrev_b32_e32 v160, 2, v80
	v_lshl_add_u64 v[0:1], v[0:1], 0, v[160:161]
	global_load_dwordx4 v[12:15], v[0:1], off nt
	global_load_dwordx4 v[8:11], v[0:1], off offset:1024 nt
	global_load_dwordx4 v[4:7], v[0:1], off offset:2048 nt
	s_nop 0
	global_load_dwordx4 v[0:3], v[0:1], off offset:3072 nt
	v_readlane_b32 s12, v253, 18
	s_mov_b32 s14, s72
	v_readlane_b32 s64, v252, 16
	s_and_b64 s[10:11], s[4:5], exec
	v_readlane_b32 s13, v253, 19
	v_readlane_b32 s65, v252, 17
	v_readlane_b32 s66, v252, 18
	v_readlane_b32 s67, v252, 19
	v_readlane_b32 s76, v252, 28
	v_readlane_b32 s77, v252, 29
	s_cselect_b32 s1, s13, 0
	s_cselect_b32 s20, s12, 0
	s_lshl_b64 s[12:13], s[58:59], 2
	v_readlane_b32 s72, v252, 24
	v_readlane_b32 s78, v252, 30
	v_readlane_b32 s79, v252, 31
	s_mov_b64 s[64:65], s[76:77]
	s_mov_b32 s72, s14
	s_add_u32 s12, s64, s12
	v_readlane_b32 s14, v253, 26
	v_xor_b32_e32 v20, 1, v197
	s_addc_u32 s13, s65, s13
	v_readlane_b32 s15, v253, 27
	v_cmp_lt_i32_e32 vcc, v20, v207
	v_xor_b32_e32 v21, 2, v197
	v_lshl_add_u64 v[82:83], s[14:15], 0, v[160:161]
	s_add_u32 s14, s20, 0x800000
	v_cndmask_b32_e32 v20, v197, v20, vcc
	v_cmp_lt_i32_e32 vcc, v21, v207
	v_xor_b32_e32 v22, 4, v197
	s_addc_u32 s15, s1, 0
	v_cndmask_b32_e32 v21, v197, v21, vcc
	v_cmp_lt_i32_e32 vcc, v22, v207
	v_xor_b32_e32 v23, 8, v197
	s_add_u32 s46, s20, 0x1000000
	v_cndmask_b32_e32 v22, v197, v22, vcc
	v_cmp_lt_i32_e32 vcc, v23, v207
	v_xor_b32_e32 v24, 16, v197
	s_mov_b64 s[66:67], s[78:79]
	s_addc_u32 s47, s1, 0
	v_cndmask_b32_e32 v23, v197, v23, vcc
	v_cmp_lt_i32_e32 vcc, v24, v207
	s_add_u32 s66, s20, 0x1800000
	v_and_b32_e32 v19, 63, v19
	v_cndmask_b32_e32 v24, v197, v24, vcc
	v_cmp_lt_i32_e32 vcc, v204, v207
	v_lshlrev_b64 v[16:17], 11, v[16:17]
	v_lshl_add_u64 v[92:93], s[12:13], 0, v[160:161]
	s_addc_u32 s67, s1, 0
	v_readlane_b32 s1, v255, 13
	v_readlane_b32 s12, v255, 14
	v_cndmask_b32_e32 v25, v197, v204, vcc
	v_lshlrev_b32_e32 v81, 2, v20
	v_lshlrev_b32_e32 v99, 2, v22
	v_lshlrev_b32_e32 v101, 2, v24
	v_or_b32_e32 v20, 0x100, v80
	v_or_b32_e32 v22, 0x200, v80
	v_or_b32_e32 v24, 0x300, v80
	v_lshl_or_b32 v16, v19, 3, v16
	s_add_i32 s1, s1, s0
	s_add_i32 s0, s12, s0
	v_lshlrev_b32_e32 v98, 2, v21
	v_lshlrev_b32_e32 v100, 2, v23
	v_lshlrev_b32_e32 v102, 2, v25
	v_lshl_add_u64 v[84:85], s[18:19], 0, v[16:17]
	v_lshlrev_b32_e32 v86, 2, v20
	v_lshlrev_b32_e32 v88, 2, v22
	v_lshlrev_b32_e32 v90, 2, v24
	v_add_u32_e32 v96, s1, v18
	v_add_u32_e32 v94, s0, v18
	s_mov_b64 s[10:11], 0
	v_lshlrev_b32_e32 v160, 2, v80
	v_ashrrev_i32_e32 v95, 31, v94
	v_readlane_b32 s68, v252, 20
	v_readlane_b32 s69, v252, 21
	v_readlane_b32 s70, v252, 22
	s_waitcnt vmcnt(0)
	v_mov_b64_e32 v[18:19], v[14:15]
	s_waitcnt vmcnt(2)
	v_mov_b64_e32 v[22:23], v[10:11]
	s_waitcnt vmcnt(1)
	v_mov_b64_e32 v[26:27], v[6:7]
	s_waitcnt vmcnt(0)
	v_mov_b64_e32 v[30:31], v[2:3]
	v_mov_b64_e32 v[16:17], v[12:13]
	v_mov_b64_e32 v[20:21], v[8:9]
	v_mov_b64_e32 v[24:25], v[4:5]
	v_mov_b64_e32 v[28:29], v[0:1]
	v_readlane_b32 s71, v252, 23
	v_readlane_b32 s73, v252, 25
	v_readlane_b32 s74, v252, 26
	v_readlane_b32 s75, v252, 27
	s_branch .LBB0_176

; #define NORM_LOADX(dst, r_) do { const int r__ = (r_); const float* xr_ = r__ < NLAT ? xlat + (size_t)r__ * DM : xctx + (size_t)(r__ - NLAT) * DM; \
;         _Pragma("unroll") for (int j = 0; j < 4; ++j) dst[j] = *(const f32x4*)(xr_ + 4 * lane + 256 * j); } while (0)
; __device__ __forceinline__ void norm_phase(const float* xlat, const float* xctx, const float* gvec, const float* mod, int sh_off, int sc_off, bf16_t* H, int nrows,
;                                            const float* part, const float* pgate, float* xctx_out, int row_lo) {
;     ...
;         if (row + NGW < nrows) NORM_LOADX(vn, row + NGW);
;         const float* mp = mod + bb * 6144;
;         f32x4 gg[4], sc[4], sh[4];
; #pragma unroll
;         for (int j = 0; j < 4; ++j) { const int col = 4 * lane + 256 * j; gg[j] = *(const f32x4*)(gvec + col); sc[j] = *(const f32x4*)(mp + sc_off + col); sh[j] = *(const f32x4*)(mp + sh_off + col); }
.LBB0_176:
	v_add_u32_e32 v103, s80, v96
	v_add_u32_e32 v32, 0x4000, v103
	s_movk_i32 s0, 0x4800
	s_movk_i32 s12, 0x47ff
	v_cmp_gt_i32_e64 s[100:101], s0, v32
	v_mov_b32_e32 v120, v32
	v_cmp_lt_i32_e32 vcc, s12, v32
	v_add_u32_e32 v97, 0x4000, v96
	v_min_i32_e32 v32, 0x4000, v97
	v_ashrrev_i32_e32 v32, 11, v32
	v_mul_i32_i24_e32 v32, 0x1800, v32
	v_ashrrev_i32_e32 v33, 31, v32
	v_lshl_add_u64 v[32:33], v[32:33], 2, s[48:49]
	s_mov_b64 s[0:1], 0x1000
	v_lshl_add_u64 v[34:35], v[32:33], 0, s[0:1]
	v_mov_b32_e32 v87, v161
	v_mov_b32_e32 v89, v161
	v_mov_b32_e32 v91, v161
	v_lshl_add_u64 v[36:37], v[34:35], 0, v[160:161]
	v_lshl_add_u64 v[32:33], v[32:33], 0, v[160:161]
	v_lshl_add_u64 v[72:73], v[34:35], 0, v[86:87]
	v_lshl_add_u64 v[40:41], v[34:35], 0, v[88:89]
	v_lshl_add_u64 v[34:35], v[34:35], 0, v[90:91]
	global_load_dwordx4 v[76:79], v[36:37], off
	global_load_dwordx4 v[64:67], v[32:33], off
	global_load_dwordx4 v[68:71], v[92:93], off
	global_load_dwordx4 v[56:59], v[92:93], off offset:1024
	global_load_dwordx4 v[60:63], v[32:33], off offset:1024
	global_load_dwordx4 v[44:47], v[32:33], off offset:2048
	global_load_dwordx4 v[48:51], v[92:93], off offset:2048
	global_load_dwordx4 v[36:39], v[92:93], off offset:3072
	global_load_dwordx4 v[52:55], v[40:41], off
	s_nop 0
	global_load_dwordx4 v[40:43], v[34:35], off
	s_nop 0
	global_load_dwordx4 v[72:75], v[72:73], off
	s_nop 0
	global_load_dwordx4 v[32:35], v[32:33], off offset:3072
	s_and_saveexec_b64 s[12:13], s[100:101]
	s_cbranch_execz .Ln1_dummy
	v_readlane_b32 s24, v255, 28
	s_movk_i32 s0, 0x4000
	v_readlane_b32 s20, v255, 30
	v_readlane_b32 s25, v255, 29
	v_cmp_gt_i32_e64 s[0:1], s0, v120
	v_mov_b32_e32 v18, s20
	v_mov_b32_e32 v19, s25
	v_readlane_b32 s20, v255, 31
	v_cndmask_b32_e64 v17, 0, v95, s[0:1]
	v_cndmask_b32_e64 v16, v103, v94, s[0:1]
	v_cndmask_b32_e64 v19, v18, v19, s[0:1]
	v_mov_b32_e32 v18, s20
	v_mov_b32_e32 v20, s24
	v_cndmask_b32_e64 v18, v18, v20, s[0:1]
	v_lshlrev_b64 v[16:17], 12, v[16:17]
	v_lshl_add_u64 v[16:17], v[18:19], 0, v[16:17]
	v_lshl_add_u64 v[28:29], v[16:17], 0, v[160:161]
	global_load_dwordx4 v[16:19], v[28:29], off nt
	global_load_dwordx4 v[20:23], v[28:29], off offset:1024 nt
	global_load_dwordx4 v[24:27], v[28:29], off offset:2048 nt
	s_nop 0
	global_load_dwordx4 v[28:31], v[28:29], off offset:3072 nt
	s_branch .Ln1_join

; #define LAS __attribute__((address_space(3)))
; #define EF_LOAD(buf, g_) do { const float* xp_ = xi + (size_t)(((g_) >> 2) * 128 + ((g_) & 3) * 16) * DM; \
;             _Pragma("unroll") for (int bj = 0; bj < 2; ++bj) _Pragma("unroll") for (int n = 0; n < 2; ++n) xv[buf][bj][n] = *(const f32x4*)(xp_ + bj * 128 + n * 4); } while (0)
;     __device__ __forceinline__ void fused(Acc& acc, const pg8::Unit& u, int wr, int wc, int fr, int fq, LAS unsigned char* lds, int wid, int lane) const {
;         const int tile0 = u.pm * 256, colb = u.pn * 256 + wc * 32 + 8 * fq, rloc = wr * 64 + fr;
;         const float* xi = xin + (size_t)(tile0 + rloc) * DM + colb;
;         float* xo = out + (size_t)(tile0 + rloc) * DM + colb;
;         const float* gp = mod + (tile0 >> 11) * 6144 + goff + colb;
;         f32x4 gt[2][2];
; #pragma unroll
;         for (int bj = 0; bj < 2; ++bj)
; #pragma unroll
;             for (int n = 0; n < 2; ++n) gt[bj][n] = *(const f32x4*)(gp + bj * 128 + n * 4);
;         f32x4 xv[1][2][2];
;     ...
;         LAS float* P = (LAS float*)lds;
;         LAS float* S = (LAS float*)(lds + 4096);
; #pragma unroll
;         for (int g_ = 0; g_ < 8; ++g_) {
;             EF_LOAD(0, g_);
;             float sq = 0.f;
; #pragma unroll
;             for (int bj = 0; bj < 2; ++bj)
; #pragma unroll
;                 for (int n = 0; n < 2; ++n) { const f32x4 xn = xv[0][bj][n] + gt[bj][n] * acc[g_ >> 2][bj][g_ & 3][n]; acc[g_ >> 2][bj][g_ & 3][n] = xn;
;                     if (MODE == 1) *(f32x4*)(xo + (size_t)((g_ >> 2) * 128 + (g_ & 3) * 16) * DM + bj * 128 + n * 4) = xn;
;                     sq += (xn[0] * xn[0] + xn[1] * xn[1]) + (xn[2] * xn[2] + xn[3] * xn[3]); }
;             sq += __shfl_xor(sq, 16); sq += __shfl_xor(sq, 32);
;             if (fq == 0) P[((g_ >> 2) * 128 + wr * 64 + (g_ & 3) * 16 + fr) * 4 + wc] = sq;
;         }
.LBB0_947:
	s_lshl_b32 s0, s9, 5
	s_lshl_b32 s1, s8, 8
	v_lshrrev_b32_e32 v128, 1, v170
	s_or_b32 s0, s1, s0
	v_and_or_b32 v154, v128, 24, s0
	s_lshr_b32 s0, s6, 3
	s_mulk_i32 s0, 0x1800
	s_ashr_i32 s1, s0, 31
	s_lshl_b32 s10, s6, 8
	s_lshl_b64 s[0:1], s[0:1], 2
	v_ashrrev_i32_e32 v155, 31, v154
	s_add_u32 s0, s48, s0
	s_addc_u32 s1, s49, s1
	v_lshlrev_b64 v[156:157], 2, v[154:155]
	v_add_u32_e32 v158, s10, v144
	v_lshl_add_u64 v[152:153], s[0:1], 0, v[156:157]
	v_ashrrev_i32_e32 v159, 31, v158
	v_add_co_u32_e32 v128, vcc, s21, v152
	v_readlane_b32 s0, v255, 28
	v_lshlrev_b64 v[150:151], 12, v[158:159]
	v_addc_co_u32_e32 v129, vcc, 0, v153, vcc
	v_readlane_b32 s1, v255, 29
	s_waitcnt vmcnt(0)
	s_barrier
	global_load_dwordx4 v[140:143], v[128:129], off
	v_lshl_add_u64 v[128:129], s[0:1], 0, v[150:151]
	v_lshl_add_u64 v[168:169], v[128:129], 0, v[156:157]
	global_load_dwordx4 v[146:149], v[168:169], off offset:16 nt
	global_load_dwordx4 v[162:165], v[168:169], off nt
	s_mov_b64 s[0:1], 0x2000
	v_lshl_add_u64 v[128:129], v[152:153], 0, s[0:1]
	global_load_dwordx4 v[136:139], v[128:129], off offset:16
	global_load_dwordx4 v[132:135], v[128:129], off offset:512
	global_load_dwordx4 v[172:175], v[168:169], off offset:512 nt
	global_load_dwordx4 v[176:179], v[168:169], off offset:528 nt
	s_nop 0
	global_load_dwordx4 v[128:131], v[128:129], off offset:528
	v_readlane_b32 s52, v252, 0
	v_readlane_b32 s54, v252, 2
	v_readlane_b32 s55, v252, 3
	s_lshl_b32 s4, s9, 2
	v_and_b32_e32 v160, 63, v170
	v_lshl_add_u64 v[150:151], s[54:55], 0, v[150:151]
	v_lshl_add_u64 v[166:167], v[150:151], 0, v[156:157]
	s_add_i32 s9, s4, 0
	v_cmp_gt_u32_e64 s[0:1], 16, v160
	v_lshl_add_u32 v144, v144, 4, s9
	v_readlane_b32 s53, v252, 1
	v_readlane_b32 s56, v252, 4
	v_readlane_b32 s57, v252, 5
	v_readlane_b32 s58, v252, 6
	v_readlane_b32 s59, v252, 7
	s_waitcnt vmcnt(0)
	v_pk_fma_f32 v[102:103], v[102:103], v[138:139], v[148:149]
	v_pk_fma_f32 v[98:99], v[98:99], v[142:143], v[164:165]
	v_pk_fma_f32 v[96:97], v[96:97], v[140:141], v[162:163]
	v_pk_fma_f32 v[100:101], v[100:101], v[136:137], v[146:147]
	v_pk_fma_f32 v[50:51], v[50:51], v[134:135], v[174:175]
	v_pk_fma_f32 v[48:49], v[48:49], v[132:133], v[172:173]
	v_mul_f32_e32 v145, v97, v97
	v_mul_f32_e32 v146, v99, v99
	v_mul_f32_e32 v147, v101, v101
	v_mul_f32_e32 v148, v103, v103
	v_pk_fma_f32 v[54:55], v[54:55], v[130:131], v[178:179]
	v_pk_fma_f32 v[52:53], v[52:53], v[128:129], v[176:177]
	v_mul_f32_e32 v149, v49, v49
	v_mul_f32_e32 v150, v51, v51
	v_fmac_f32_e32 v145, v96, v96
	v_fmac_f32_e32 v146, v98, v98
	v_fmac_f32_e32 v147, v100, v100
	v_fmac_f32_e32 v148, v102, v102
	v_mul_f32_e32 v151, v53, v53
	v_mul_f32_e32 v162, v55, v55
	v_fmac_f32_e32 v149, v48, v48
	v_fmac_f32_e32 v150, v50, v50
	v_add_f32_e32 v145, v145, v146
	v_add_f32_e32 v146, v147, v148
	v_fmac_f32_e32 v151, v52, v52
	v_fmac_f32_e32 v162, v54, v54
	v_add_f32_e32 v147, v149, v150
	v_add_f32_e32 v145, v145, v146
	v_add_f32_e32 v145, v145, v147
	v_add_f32_e32 v146, v151, v162
	v_add_f32_e32 v145, v145, v146
	ds_bpermute_b32 v146, v213, v145
	s_waitcnt lgkmcnt(0)
	v_add_f32_e32 v145, v145, v146
	ds_bpermute_b32 v146, v214, v145
	s_and_saveexec_b64 s[4:5], s[0:1]
	s_cbranch_execz .LBB0_949
	s_waitcnt lgkmcnt(0)
	v_add_f32_e32 v145, v145, v146
	ds_write_b32 v144, v145
.LBB0_949:
	s_or_b64 exec, exec, s[4:5]
	v_add_co_u32_e32 v150, vcc, 0x10000, v168
	v_lshl_add_u64 v[162:163], v[168:169], 0, s[88:89]
	s_nop 0
	v_addc_co_u32_e32 v151, vcc, 0, v169, vcc
	s_waitcnt lgkmcnt(0)
	global_load_dwordx4 v[146:149], v[150:151], off nt
	s_mov_b64 s[4:5], 0x10200
	global_load_dwordx4 v[162:165], v[162:163], off offset:16 nt
	s_nop 0
	global_load_dwordx4 v[172:175], v[150:151], off offset:512 nt
	v_lshl_add_u64 v[150:151], v[168:169], 0, s[4:5]
	global_load_dwordx4 v[176:179], v[150:151], off offset:16 nt
	s_mov_b32 s4, 0x10000
	s_waitcnt vmcnt(3)
	v_pk_fma_f32 v[106:107], v[106:107], v[142:143], v[148:149]
	v_pk_fma_f32 v[104:105], v[104:105], v[140:141], v[146:147]
	s_waitcnt vmcnt(2)
	v_pk_fma_f32 v[114:115], v[114:115], v[138:139], v[164:165]
	v_pk_fma_f32 v[112:113], v[112:113], v[136:137], v[162:163]
	s_waitcnt vmcnt(1)
	v_pk_fma_f32 v[66:67], v[66:67], v[134:135], v[174:175]
	v_pk_fma_f32 v[64:65], v[64:65], v[132:133], v[172:173]
	v_mul_f32_e32 v145, v105, v105
	v_mul_f32_e32 v146, v107, v107
	v_mul_f32_e32 v147, v113, v113
	v_mul_f32_e32 v148, v115, v115
	s_waitcnt vmcnt(0)
	v_pk_fma_f32 v[74:75], v[74:75], v[130:131], v[178:179]
	v_pk_fma_f32 v[72:73], v[72:73], v[128:129], v[176:177]
	v_mul_f32_e32 v149, v65, v65
	v_mul_f32_e32 v150, v67, v67
	v_fmac_f32_e32 v145, v104, v104
	v_fmac_f32_e32 v146, v106, v106
	v_fmac_f32_e32 v147, v112, v112
	v_fmac_f32_e32 v148, v114, v114
	v_mul_f32_e32 v151, v73, v73
	v_mul_f32_e32 v162, v75, v75
	v_fmac_f32_e32 v149, v64, v64
	v_fmac_f32_e32 v150, v66, v66
	v_add_f32_e32 v145, v145, v146
	v_add_f32_e32 v146, v147, v148
	v_fmac_f32_e32 v151, v72, v72
	v_fmac_f32_e32 v162, v74, v74
	v_add_f32_e32 v147, v149, v150
	v_add_f32_e32 v145, v145, v146
	v_add_f32_e32 v148, v151, v162
	v_add_f32_e32 v145, v145, v147
	v_add_f32_e32 v145, v145, v148
	ds_bpermute_b32 v146, v213, v145
	v_add_co_u32_e32 v216, vcc, s4, v166
	s_waitcnt lgkmcnt(0)
	v_add_f32_e32 v145, v145, v146
	ds_bpermute_b32 v146, v214, v145
	v_addc_co_u32_e32 v217, vcc, 0, v167, vcc
	s_and_saveexec_b64 s[4:5], s[0:1]
	v_readlane_b32 s24, v255, 38
	v_readlane_b32 s25, v255, 39
	s_mov_b64 s[34:35], s[60:61]
	s_cbranch_execz .LBB0_951
	s_waitcnt lgkmcnt(0)
	v_add_f32_e32 v145, v145, v146
	ds_write_b32 v144, v145 offset:256
; #define LAS __attribute__((address_space(3)))
; #define EF_LOAD(buf, g_) do { const float* xp_ = xi + (size_t)(((g_) >> 2) * 128 + ((g_) & 3) * 16) * DM; \
;             _Pragma("unroll") for (int bj = 0; bj < 2; ++bj) _Pragma("unroll") for (int n = 0; n < 2; ++n) xv[buf][bj][n] = *(const f32x4*)(xp_ + bj * 128 + n * 4); } while (0)
;     __device__ __forceinline__ void fused(Acc& acc, const pg8::Unit& u, int wr, int wc, int fr, int fq, LAS unsigned char* lds, int wid, int lane) const {
;     ...
;         LAS float* P = (LAS float*)lds;
;         LAS float* S = (LAS float*)(lds + 4096);
; #pragma unroll
;         for (int g_ = 0; g_ < 8; ++g_) {
;             EF_LOAD(0, g_);
;             float sq = 0.f;
; #pragma unroll
;             for (int bj = 0; bj < 2; ++bj)
; #pragma unroll
;                 for (int n = 0; n < 2; ++n) { const f32x4 xn = xv[0][bj][n] + gt[bj][n] * acc[g_ >> 2][bj][g_ & 3][n]; acc[g_ >> 2][bj][g_ & 3][n] = xn;
;                     if (MODE == 1) *(f32x4*)(xo + (size_t)((g_ >> 2) * 128 + (g_ & 3) * 16) * DM + bj * 128 + n * 4) = xn;
;                     sq += (xn[0] * xn[0] + xn[1] * xn[1]) + (xn[2] * xn[2] + xn[3] * xn[3]); }
;             sq += __shfl_xor(sq, 16); sq += __shfl_xor(sq, 32);
;             if (fq == 0) P[((g_ >> 2) * 128 + wr * 64 + (g_ & 3) * 16 + fr) * 4 + wc] = sq;
;         }
.LBB0_951:
	s_or_b64 exec, exec, s[4:5]
	v_add_co_u32_e32 v150, vcc, 0x20000, v168
	s_mov_b64 s[4:5], 0x20000
	s_nop 0
	v_addc_co_u32_e32 v151, vcc, 0, v169, vcc
	s_waitcnt lgkmcnt(0)
	global_load_dwordx4 v[146:149], v[150:151], off nt
	v_lshl_add_u64 v[162:163], v[168:169], 0, s[4:5]
	s_mov_b64 s[4:5], 0x20200
	global_load_dwordx4 v[162:165], v[162:163], off offset:16 nt
	s_nop 0
	global_load_dwordx4 v[172:175], v[150:151], off offset:512 nt
	v_lshl_add_u64 v[150:151], v[168:169], 0, s[4:5]
	global_load_dwordx4 v[176:179], v[150:151], off offset:16 nt
	s_mov_b32 s4, 0x20000
	s_waitcnt vmcnt(3)
	v_pk_fma_f32 v[122:123], v[122:123], v[142:143], v[148:149]
	v_pk_fma_f32 v[120:121], v[120:121], v[140:141], v[146:147]
	s_waitcnt vmcnt(2)
	v_pk_fma_f32 v[126:127], v[126:127], v[138:139], v[164:165]
	v_pk_fma_f32 v[124:125], v[124:125], v[136:137], v[162:163]
	s_waitcnt vmcnt(1)
	v_pk_fma_f32 v[82:83], v[82:83], v[134:135], v[174:175]
	v_pk_fma_f32 v[80:81], v[80:81], v[132:133], v[172:173]
	v_mul_f32_e32 v145, v121, v121
	v_mul_f32_e32 v146, v123, v123
	v_mul_f32_e32 v147, v125, v125
	v_mul_f32_e32 v148, v127, v127
	s_waitcnt vmcnt(0)
	v_pk_fma_f32 v[90:91], v[90:91], v[130:131], v[178:179]
	v_pk_fma_f32 v[88:89], v[88:89], v[128:129], v[176:177]
	v_mul_f32_e32 v149, v81, v81
	v_mul_f32_e32 v150, v83, v83
	v_fmac_f32_e32 v145, v120, v120
	v_fmac_f32_e32 v146, v122, v122
	v_fmac_f32_e32 v147, v124, v124
	v_fmac_f32_e32 v148, v126, v126
	v_mul_f32_e32 v151, v89, v89
	v_mul_f32_e32 v162, v91, v91
	v_fmac_f32_e32 v149, v80, v80
	v_fmac_f32_e32 v150, v82, v82
	v_add_f32_e32 v145, v145, v146
	v_add_f32_e32 v146, v147, v148
	v_fmac_f32_e32 v151, v88, v88
	v_fmac_f32_e32 v162, v90, v90
	v_add_f32_e32 v147, v149, v150
	v_add_f32_e32 v145, v145, v146
	v_add_f32_e32 v148, v151, v162
	v_add_f32_e32 v145, v145, v147
	v_add_f32_e32 v145, v145, v148
	ds_bpermute_b32 v146, v213, v145
	v_add_co_u32_e32 v218, vcc, s4, v166
	s_waitcnt lgkmcnt(0)
	v_add_f32_e32 v145, v145, v146
	ds_bpermute_b32 v146, v214, v145
	v_addc_co_u32_e32 v219, vcc, 0, v167, vcc
	s_and_saveexec_b64 s[4:5], s[0:1]
	s_cbranch_execz .LBB0_953
	s_waitcnt lgkmcnt(0)
	v_add_f32_e32 v145, v145, v146
	ds_write_b32 v144, v145 offset:512
.LBB0_953:
	s_or_b64 exec, exec, s[4:5]
	v_add_co_u32_e32 v150, vcc, 0x30000, v168
	s_mov_b64 s[4:5], 0x30000
	s_nop 0
	v_addc_co_u32_e32 v151, vcc, 0, v169, vcc
	s_waitcnt lgkmcnt(0)
	global_load_dwordx4 v[146:149], v[150:151], off nt
	v_lshl_add_u64 v[162:163], v[168:169], 0, s[4:5]
	s_mov_b64 s[4:5], 0x30200
	global_load_dwordx4 v[162:165], v[162:163], off offset:16 nt
	s_nop 0
	global_load_dwordx4 v[172:175], v[150:151], off offset:512 nt
	v_lshl_add_u64 v[150:151], v[168:169], 0, s[4:5]
	global_load_dwordx4 v[176:179], v[150:151], off offset:16 nt
	s_mov_b32 s4, 0x30000
	s_waitcnt vmcnt(3)
	v_pk_fma_f32 v[118:119], v[118:119], v[142:143], v[148:149]
	v_pk_fma_f32 v[116:117], v[116:117], v[140:141], v[146:147]
	s_waitcnt vmcnt(2)
	v_pk_fma_f32 v[110:111], v[110:111], v[138:139], v[164:165]
	v_pk_fma_f32 v[108:109], v[108:109], v[136:137], v[162:163]
	s_waitcnt vmcnt(1)
	v_pk_fma_f32 v[94:95], v[94:95], v[134:135], v[174:175]
	v_pk_fma_f32 v[92:93], v[92:93], v[132:133], v[172:173]
	v_mul_f32_e32 v145, v117, v117
	v_mul_f32_e32 v146, v119, v119
	v_mul_f32_e32 v147, v109, v109
	v_mul_f32_e32 v148, v111, v111
	s_waitcnt vmcnt(0)
	v_pk_fma_f32 v[86:87], v[86:87], v[130:131], v[178:179]
	v_pk_fma_f32 v[84:85], v[84:85], v[128:129], v[176:177]
	v_mul_f32_e32 v149, v93, v93
	v_mul_f32_e32 v150, v95, v95
	v_fmac_f32_e32 v145, v116, v116
	v_fmac_f32_e32 v146, v118, v118
	v_fmac_f32_e32 v147, v108, v108
	v_fmac_f32_e32 v148, v110, v110
	v_mul_f32_e32 v151, v85, v85
	v_mul_f32_e32 v162, v87, v87
	v_fmac_f32_e32 v149, v92, v92
	v_fmac_f32_e32 v150, v94, v94
	v_add_f32_e32 v145, v145, v146
	v_add_f32_e32 v146, v147, v148
	v_fmac_f32_e32 v151, v84, v84
	v_fmac_f32_e32 v162, v86, v86
	v_add_f32_e32 v147, v149, v150
	v_add_f32_e32 v145, v145, v146
	v_add_f32_e32 v148, v151, v162
	v_add_f32_e32 v145, v145, v147
	v_add_f32_e32 v145, v145, v148
	ds_bpermute_b32 v146, v213, v145
	v_add_co_u32_e32 v220, vcc, s4, v166
	s_waitcnt lgkmcnt(0)
	v_add_f32_e32 v145, v145, v146
	ds_bpermute_b32 v146, v214, v145
	v_addc_co_u32_e32 v221, vcc, 0, v167, vcc
	s_and_saveexec_b64 s[4:5], s[0:1]
	s_cbranch_execz .LBB0_955
	s_waitcnt lgkmcnt(0)
	v_add_f32_e32 v145, v145, v146
	ds_write_b32 v144, v145 offset:768
.LBB0_955:
	s_or_b64 exec, exec, s[4:5]
	v_add_co_u32_e32 v162, vcc, 0x80000, v168
	s_mov_b64 s[4:5], 0x80000
	s_nop 0
	v_addc_co_u32_e32 v163, vcc, 0, v169, vcc
	s_waitcnt lgkmcnt(0)
	global_load_dwordx4 v[144:147], v[162:163], off nt
	v_lshl_add_u64 v[148:149], v[168:169], 0, s[4:5]
	s_mov_b64 s[4:5], 0x80200
	global_load_dwordx4 v[148:151], v[148:149], off offset:16 nt
	s_nop 0
	global_load_dwordx4 v[162:165], v[162:163], off offset:512 nt
	v_lshl_add_u64 v[172:173], v[168:169], 0, s[4:5]
	global_load_dwordx4 v[172:175], v[172:173], off offset:16 nt
	s_mov_b32 s4, 0x80000
	s_waitcnt vmcnt(3)
	v_pk_fma_f32 v[78:79], v[78:79], v[142:143], v[146:147]
	v_pk_fma_f32 v[76:77], v[76:77], v[140:141], v[144:145]
	s_waitcnt vmcnt(2)
	v_pk_fma_f32 v[70:71], v[70:71], v[138:139], v[150:151]
	v_pk_fma_f32 v[68:69], v[68:69], v[136:137], v[148:149]
	s_waitcnt vmcnt(1)
	v_pk_fma_f32 v[62:63], v[62:63], v[134:135], v[164:165]
	v_pk_fma_f32 v[60:61], v[60:61], v[132:133], v[162:163]
	v_mul_f32_e32 v144, v77, v77
	v_mul_f32_e32 v145, v79, v79
	v_mul_f32_e32 v146, v69, v69
	v_mul_f32_e32 v147, v71, v71
	s_waitcnt vmcnt(0)
	v_pk_fma_f32 v[58:59], v[58:59], v[130:131], v[174:175]
	v_pk_fma_f32 v[56:57], v[56:57], v[128:129], v[172:173]
	v_mul_f32_e32 v148, v61, v61
	v_mul_f32_e32 v149, v63, v63
	v_fmac_f32_e32 v144, v76, v76
	v_fmac_f32_e32 v145, v78, v78
	v_fmac_f32_e32 v146, v68, v68
	v_fmac_f32_e32 v147, v70, v70
	v_mul_f32_e32 v150, v57, v57
	v_mul_f32_e32 v151, v59, v59
	v_fmac_f32_e32 v148, v60, v60
	v_fmac_f32_e32 v149, v62, v62
	v_add_f32_e32 v144, v144, v145
	v_add_f32_e32 v145, v146, v147
	v_fmac_f32_e32 v150, v56, v56
	v_fmac_f32_e32 v151, v58, v58
	v_add_f32_e32 v146, v148, v149
	v_add_f32_e32 v144, v144, v145
	v_add_f32_e32 v147, v150, v151
	v_add_f32_e32 v144, v144, v146
	v_add_f32_e32 v144, v144, v147
	ds_bpermute_b32 v145, v213, v144
	v_add_co_u32_e32 v222, vcc, s4, v166
	s_waitcnt lgkmcnt(0)
	v_add_f32_e32 v144, v144, v145
	ds_bpermute_b32 v145, v214, v144
	v_addc_co_u32_e32 v223, vcc, 0, v167, vcc
	s_and_saveexec_b64 s[4:5], s[0:1]
	s_cbranch_execz .LBB0_957
	s_add_i32 s11, s7, 0x80
	v_or_b32_e32 v146, s11, v171
	v_lshl_add_u32 v146, v146, 4, s9
	s_waitcnt lgkmcnt(0)
	v_add_f32_e32 v144, v144, v145
	ds_write_b32 v146, v144
; #define LAS __attribute__((address_space(3)))
; #define EF_LOAD(buf, g_) do { const float* xp_ = xi + (size_t)(((g_) >> 2) * 128 + ((g_) & 3) * 16) * DM; \
;             _Pragma("unroll") for (int bj = 0; bj < 2; ++bj) _Pragma("unroll") for (int n = 0; n < 2; ++n) xv[buf][bj][n] = *(const f32x4*)(xp_ + bj * 128 + n * 4); } while (0)
;     __device__ __forceinline__ void fused(Acc& acc, const pg8::Unit& u, int wr, int wc, int fr, int fq, LAS unsigned char* lds, int wid, int lane) const {
;     ...
;         LAS float* P = (LAS float*)lds;
;         LAS float* S = (LAS float*)(lds + 4096);
; #pragma unroll
;         for (int g_ = 0; g_ < 8; ++g_) {
;             EF_LOAD(0, g_);
;             float sq = 0.f;
; #pragma unroll
;             for (int bj = 0; bj < 2; ++bj)
; #pragma unroll
;                 for (int n = 0; n < 2; ++n) { const f32x4 xn = xv[0][bj][n] + gt[bj][n] * acc[g_ >> 2][bj][g_ & 3][n]; acc[g_ >> 2][bj][g_ & 3][n] = xn;
;                     if (MODE == 1) *(f32x4*)(xo + (size_t)((g_ >> 2) * 128 + (g_ & 3) * 16) * DM + bj * 128 + n * 4) = xn;
;                     sq += (xn[0] * xn[0] + xn[1] * xn[1]) + (xn[2] * xn[2] + xn[3] * xn[3]); }
;             sq += __shfl_xor(sq, 16); sq += __shfl_xor(sq, 32);
;             if (fq == 0) P[((g_ >> 2) * 128 + wr * 64 + (g_ & 3) * 16 + fr) * 4 + wc] = sq;
;         }
.LBB0_957:
	s_or_b64 exec, exec, s[4:5]
	v_add_co_u32_e32 v162, vcc, 0x90000, v168
	s_mov_b64 s[4:5], 0x90000
	s_nop 0
	v_addc_co_u32_e32 v163, vcc, 0, v169, vcc
	s_waitcnt lgkmcnt(0)
	global_load_dwordx4 v[144:147], v[162:163], off nt
	v_lshl_add_u64 v[148:149], v[168:169], 0, s[4:5]
	s_mov_b64 s[4:5], 0x90200
	global_load_dwordx4 v[148:151], v[148:149], off offset:16 nt
	s_nop 0
	global_load_dwordx4 v[162:165], v[162:163], off offset:512 nt
	v_lshl_add_u64 v[172:173], v[168:169], 0, s[4:5]
	global_load_dwordx4 v[172:175], v[172:173], off offset:16 nt
	s_mov_b32 s4, 0x90000
	s_waitcnt vmcnt(3)
	v_pk_fma_f32 v[46:47], v[46:47], v[142:143], v[146:147]
	v_pk_fma_f32 v[44:45], v[44:45], v[140:141], v[144:145]
	s_waitcnt vmcnt(2)
	v_pk_fma_f32 v[42:43], v[42:43], v[138:139], v[150:151]
	v_pk_fma_f32 v[40:41], v[40:41], v[136:137], v[148:149]
	s_waitcnt vmcnt(1)
	v_pk_fma_f32 v[38:39], v[38:39], v[134:135], v[164:165]
	v_pk_fma_f32 v[36:37], v[36:37], v[132:133], v[162:163]
	v_mul_f32_e32 v144, v45, v45
	v_mul_f32_e32 v145, v47, v47
	v_mul_f32_e32 v146, v41, v41
	v_mul_f32_e32 v147, v43, v43
	s_waitcnt vmcnt(0)
	v_pk_fma_f32 v[34:35], v[34:35], v[130:131], v[174:175]
	v_pk_fma_f32 v[32:33], v[32:33], v[128:129], v[172:173]
	v_mul_f32_e32 v148, v37, v37
	v_mul_f32_e32 v149, v39, v39
	v_fmac_f32_e32 v144, v44, v44
	v_fmac_f32_e32 v145, v46, v46
	v_fmac_f32_e32 v146, v40, v40
	v_fmac_f32_e32 v147, v42, v42
	v_mul_f32_e32 v150, v33, v33
	v_mul_f32_e32 v151, v35, v35
	v_fmac_f32_e32 v148, v36, v36
	v_fmac_f32_e32 v149, v38, v38
	v_add_f32_e32 v144, v144, v145
	v_add_f32_e32 v145, v146, v147
	v_fmac_f32_e32 v150, v32, v32
	v_fmac_f32_e32 v151, v34, v34
	v_add_f32_e32 v146, v148, v149
	v_add_f32_e32 v144, v144, v145
	v_add_f32_e32 v147, v150, v151
	v_add_f32_e32 v144, v144, v146
	v_add_f32_e32 v144, v144, v147
	ds_bpermute_b32 v145, v213, v144
	v_add_co_u32_e32 v224, vcc, s4, v166
	s_waitcnt lgkmcnt(0)
	v_add_f32_e32 v144, v144, v145
	ds_bpermute_b32 v145, v214, v144
	v_addc_co_u32_e32 v225, vcc, 0, v167, vcc
	s_and_saveexec_b64 s[4:5], s[0:1]
	s_cbranch_execz .LBB0_959
	s_add_i32 s11, s7, 0x90
	v_or_b32_e32 v146, s11, v171
	v_lshl_add_u32 v146, v146, 4, s9
	s_waitcnt lgkmcnt(0)
	v_add_f32_e32 v144, v144, v145
	ds_write_b32 v146, v144
.LBB0_959:
	s_or_b64 exec, exec, s[4:5]
	v_add_co_u32_e32 v162, vcc, 0xa0000, v168
	s_mov_b64 s[4:5], 0xa0000
	s_nop 0
	v_addc_co_u32_e32 v163, vcc, 0, v169, vcc
	v_lshl_add_u64 v[148:149], v[168:169], 0, s[4:5]
	s_mov_b64 s[4:5], 0xa0200
	s_waitcnt lgkmcnt(0)
	global_load_dwordx4 v[144:147], v[162:163], off nt
	v_lshl_add_u64 v[172:173], v[168:169], 0, s[4:5]
	global_load_dwordx4 v[148:151], v[148:149], off offset:16 nt
	s_nop 0
	global_load_dwordx4 v[162:165], v[162:163], off offset:512 nt
	s_mov_b32 s4, 0xa0000
	global_load_dwordx4 v[172:175], v[172:173], off offset:16 nt
	s_waitcnt vmcnt(3)
	v_pk_fma_f32 v[146:147], v[30:31], v[142:143], v[146:147]
	v_pk_fma_f32 v[144:145], v[28:29], v[140:141], v[144:145]
	s_waitcnt vmcnt(2)
	v_pk_fma_f32 v[150:151], v[26:27], v[138:139], v[150:151]
	v_pk_fma_f32 v[148:149], v[24:25], v[136:137], v[148:149]
	s_waitcnt vmcnt(1)
	v_pk_fma_f32 v[26:27], v[22:23], v[134:135], v[164:165]
	v_pk_fma_f32 v[24:25], v[20:21], v[132:133], v[162:163]
	s_waitcnt vmcnt(0)
	v_pk_fma_f32 v[30:31], v[18:19], v[130:131], v[174:175]
	v_pk_fma_f32 v[28:29], v[16:17], v[128:129], v[172:173]
	v_mul_f32_e32 v16, v145, v145
	v_mul_f32_e32 v17, v147, v147
	v_mul_f32_e32 v18, v149, v149
	v_mul_f32_e32 v19, v151, v151
	v_mul_f32_e32 v20, v25, v25
	v_mul_f32_e32 v21, v27, v27
	v_fmac_f32_e32 v16, v144, v144
	v_fmac_f32_e32 v17, v146, v146
	v_fmac_f32_e32 v18, v148, v148
	v_fmac_f32_e32 v19, v150, v150
	v_mul_f32_e32 v22, v29, v29
	v_mul_f32_e32 v23, v31, v31
	v_fmac_f32_e32 v20, v24, v24
	v_fmac_f32_e32 v21, v26, v26
	v_add_f32_e32 v16, v16, v17
	v_add_f32_e32 v17, v18, v19
	v_fmac_f32_e32 v22, v28, v28
	v_fmac_f32_e32 v23, v30, v30
	v_add_f32_e32 v18, v20, v21
	v_add_f32_e32 v16, v16, v17
	v_add_f32_e32 v19, v22, v23
	v_add_f32_e32 v16, v16, v18
	v_add_f32_e32 v16, v16, v19
	ds_bpermute_b32 v17, v213, v16
	v_add_co_u32_e32 v226, vcc, s4, v166
	s_waitcnt lgkmcnt(0)
	v_add_f32_e32 v16, v16, v17
	ds_bpermute_b32 v17, v214, v16
	v_addc_co_u32_e32 v227, vcc, 0, v167, vcc
	s_and_saveexec_b64 s[4:5], s[0:1]
	s_cbranch_execz .LBB0_961
	s_add_i32 s11, s7, 0xa0
	v_or_b32_e32 v18, s11, v171
	v_lshl_add_u32 v18, v18, 4, s9
	s_waitcnt lgkmcnt(0)
	v_add_f32_e32 v16, v16, v17
	ds_write_b32 v18, v16
; #define LAS __attribute__((address_space(3)))
; #define EF_LOAD(buf, g_) do { const float* xp_ = xi + (size_t)(((g_) >> 2) * 128 + ((g_) & 3) * 16) * DM; \
;             _Pragma("unroll") for (int bj = 0; bj < 2; ++bj) _Pragma("unroll") for (int n = 0; n < 2; ++n) xv[buf][bj][n] = *(const f32x4*)(xp_ + bj * 128 + n * 4); } while (0)
;     __device__ __forceinline__ void fused(Acc& acc, const pg8::Unit& u, int wr, int wc, int fr, int fq, LAS unsigned char* lds, int wid, int lane) const {
;     ...
;         LAS float* P = (LAS float*)lds;
;         LAS float* S = (LAS float*)(lds + 4096);
; #pragma unroll
;         for (int g_ = 0; g_ < 8; ++g_) {
;             EF_LOAD(0, g_);
;             float sq = 0.f;
; #pragma unroll
;             for (int bj = 0; bj < 2; ++bj)
; #pragma unroll
;                 for (int n = 0; n < 2; ++n) { const f32x4 xn = xv[0][bj][n] + gt[bj][n] * acc[g_ >> 2][bj][g_ & 3][n]; acc[g_ >> 2][bj][g_ & 3][n] = xn;
;                     if (MODE == 1) *(f32x4*)(xo + (size_t)((g_ >> 2) * 128 + (g_ & 3) * 16) * DM + bj * 128 + n * 4) = xn;
;                     sq += (xn[0] * xn[0] + xn[1] * xn[1]) + (xn[2] * xn[2] + xn[3] * xn[3]); }
;             sq += __shfl_xor(sq, 16); sq += __shfl_xor(sq, 32);
;             if (fq == 0) P[((g_ >> 2) * 128 + wr * 64 + (g_ & 3) * 16 + fr) * 4 + wc] = sq;
;         }
.LBB0_961:
	s_or_b64 exec, exec, s[4:5]
	v_add_co_u32_e32 v162, vcc, 0xb0000, v168
	s_mov_b64 s[4:5], 0xb0000
	s_nop 0
	v_addc_co_u32_e32 v163, vcc, 0, v169, vcc
	s_waitcnt lgkmcnt(0)
	global_load_dwordx4 v[16:19], v[162:163], off nt
	v_lshl_add_u64 v[20:21], v[168:169], 0, s[4:5]
	s_mov_b64 s[4:5], 0xb0200
	global_load_dwordx4 v[20:23], v[20:21], off offset:16 nt
	s_nop 0
	global_load_dwordx4 v[162:165], v[162:163], off offset:512 nt
	v_lshl_add_u64 v[168:169], v[168:169], 0, s[4:5]
	global_load_dwordx4 v[172:175], v[168:169], off offset:16 nt
	s_mov_b32 s4, 0xb0000
	s_waitcnt vmcnt(3)
	v_pk_fma_f32 v[14:15], v[14:15], v[142:143], v[18:19]
	v_pk_fma_f32 v[12:13], v[12:13], v[140:141], v[16:17]
	s_waitcnt vmcnt(2)
	v_pk_fma_f32 v[10:11], v[10:11], v[138:139], v[22:23]
	v_pk_fma_f32 v[8:9], v[8:9], v[136:137], v[20:21]
	s_waitcnt vmcnt(1)
	v_pk_fma_f32 v[2:3], v[2:3], v[134:135], v[164:165]
	v_pk_fma_f32 v[0:1], v[0:1], v[132:133], v[162:163]
	v_mul_f32_e32 v16, v13, v13
	v_mul_f32_e32 v17, v15, v15
	v_mul_f32_e32 v18, v9, v9
	v_mul_f32_e32 v19, v11, v11
	s_waitcnt vmcnt(0)
	v_pk_fma_f32 v[6:7], v[6:7], v[130:131], v[174:175]
	v_pk_fma_f32 v[4:5], v[4:5], v[128:129], v[172:173]
	v_mul_f32_e32 v20, v1, v1
	v_mul_f32_e32 v21, v3, v3
	v_fmac_f32_e32 v16, v12, v12
	v_fmac_f32_e32 v17, v14, v14
	v_fmac_f32_e32 v18, v8, v8
	v_fmac_f32_e32 v19, v10, v10
	v_mul_f32_e32 v22, v5, v5
	v_mul_f32_e32 v23, v7, v7
	v_fmac_f32_e32 v20, v0, v0
	v_fmac_f32_e32 v21, v2, v2
	v_add_f32_e32 v16, v16, v17
	v_add_f32_e32 v17, v18, v19
	v_fmac_f32_e32 v22, v4, v4
	v_fmac_f32_e32 v23, v6, v6
	v_add_f32_e32 v18, v20, v21
	v_add_f32_e32 v16, v16, v17
	v_add_f32_e32 v19, v22, v23
	v_add_f32_e32 v16, v16, v18
	v_add_f32_e32 v16, v16, v19
	ds_bpermute_b32 v17, v213, v16
	v_add_co_u32_e32 v18, vcc, s4, v166
	s_waitcnt lgkmcnt(0)
	v_add_f32_e32 v16, v16, v17
	ds_bpermute_b32 v17, v214, v16
	v_addc_co_u32_e32 v19, vcc, 0, v167, vcc
	global_store_dwordx4 v[166:167], v[96:99], off
	global_store_dwordx4 v[166:167], v[100:103], off offset:16
	global_store_dwordx4 v[166:167], v[48:51], off offset:512
	global_store_dwordx4 v[166:167], v[52:55], off offset:528
	global_store_dwordx4 v[216:217], v[104:107], off
	global_store_dwordx4 v[216:217], v[112:115], off offset:16
	global_store_dwordx4 v[216:217], v[64:67], off offset:512
	global_store_dwordx4 v[216:217], v[72:75], off offset:528
	global_store_dwordx4 v[218:219], v[120:123], off
	global_store_dwordx4 v[218:219], v[124:127], off offset:16
	global_store_dwordx4 v[218:219], v[80:83], off offset:512
	global_store_dwordx4 v[218:219], v[88:91], off offset:528
	global_store_dwordx4 v[220:221], v[116:119], off
	global_store_dwordx4 v[220:221], v[108:111], off offset:16
	global_store_dwordx4 v[220:221], v[92:95], off offset:512
	global_store_dwordx4 v[220:221], v[84:87], off offset:528
	global_store_dwordx4 v[222:223], v[76:79], off
	global_store_dwordx4 v[222:223], v[68:71], off offset:16
	global_store_dwordx4 v[222:223], v[60:63], off offset:512
	global_store_dwordx4 v[222:223], v[56:59], off offset:528
	global_store_dwordx4 v[224:225], v[44:47], off
	global_store_dwordx4 v[224:225], v[40:43], off offset:16
	global_store_dwordx4 v[224:225], v[36:39], off offset:512
	global_store_dwordx4 v[224:225], v[32:35], off offset:528
	global_store_dwordx4 v[226:227], v[144:147], off
	global_store_dwordx4 v[226:227], v[148:151], off offset:16
	global_store_dwordx4 v[226:227], v[24:27], off offset:512
	global_store_dwordx4 v[226:227], v[28:31], off offset:528
	global_store_dwordx4 v[18:19], v[12:15], off
	global_store_dwordx4 v[18:19], v[8:11], off offset:16
	global_store_dwordx4 v[18:19], v[0:3], off offset:512
	global_store_dwordx4 v[18:19], v[4:7], off offset:528
	s_and_saveexec_b64 s[4:5], s[0:1]
	s_cbranch_execz .LBB0_963
	s_add_i32 s0, s7, 0xb0
	v_or_b32_e32 v18, s0, v171
	v_lshl_add_u32 v18, v18, 4, s9
	s_waitcnt lgkmcnt(0)
	v_add_f32_e32 v16, v16, v17
	ds_write_b32 v18, v16

; #define LAS __attribute__((address_space(3)))
; #define EF_LOAD(buf, g_) do { const float* xp_ = xi + (size_t)(((g_) >> 2) * 128 + ((g_) & 3) * 16) * DM; \
;             _Pragma("unroll") for (int bj = 0; bj < 2; ++bj) _Pragma("unroll") for (int n = 0; n < 2; ++n) xv[buf][bj][n] = *(const f32x4*)(xp_ + bj * 128 + n * 4); } while (0)
;     __device__ __forceinline__ void fused(Acc& acc, const pg8::Unit& u, int wr, int wc, int fr, int fq, LAS unsigned char* lds, int wid, int lane) const {
;         const int tile0 = u.pm * 256, colb = u.pn * 256 + wc * 32 + 8 * fq, rloc = wr * 64 + fr;
;         const float* xi = xin + (size_t)(tile0 + rloc) * DM + colb;
;         float* xo = out + (size_t)(tile0 + rloc) * DM + colb;
;         const float* gp = mod + (tile0 >> 11) * 6144 + goff + colb;
;         f32x4 gt[2][2];
; #pragma unroll
;         for (int bj = 0; bj < 2; ++bj)
; #pragma unroll
;             for (int n = 0; n < 2; ++n) gt[bj][n] = *(const f32x4*)(gp + bj * 128 + n * 4);
;         f32x4 xv[1][2][2];
;     ...
;         LAS float* P = (LAS float*)lds;
;         LAS float* S = (LAS float*)(lds + 4096);
; #pragma unroll
;         for (int g_ = 0; g_ < 8; ++g_) {
;             EF_LOAD(0, g_);
;             float sq = 0.f;
; #pragma unroll
;             for (int bj = 0; bj < 2; ++bj)
; #pragma unroll
;                 for (int n = 0; n < 2; ++n) { const f32x4 xn = xv[0][bj][n] + gt[bj][n] * acc[g_ >> 2][bj][g_ & 3][n]; acc[g_ >> 2][bj][g_ & 3][n] = xn;
;                     if (MODE == 1) *(f32x4*)(xo + (size_t)((g_ >> 2) * 128 + (g_ & 3) * 16) * DM + bj * 128 + n * 4) = xn;
;                     sq += (xn[0] * xn[0] + xn[1] * xn[1]) + (xn[2] * xn[2] + xn[3] * xn[3]); }
;             sq += __shfl_xor(sq, 16); sq += __shfl_xor(sq, 32);
;             if (fq == 0) P[((g_ >> 2) * 128 + wr * 64 + (g_ & 3) * 16 + fr) * 4 + wc] = sq;
;         }
.LBB0_1051:
	s_lshr_b32 s12, s96, 3
	s_mulk_i32 s12, 0x1800
	s_ashr_i32 s13, s12, 31
	s_lshl_b64 s[12:13], s[12:13], 2
	s_add_u32 s12, s48, s12
	s_addc_u32 s13, s49, s13
	v_lshlrev_b64 v[174:175], 2, v[172:173]
	v_add_u32_e32 v176, s34, v158
	v_lshl_add_u64 v[170:171], s[12:13], 0, v[174:175]
	v_ashrrev_i32_e32 v177, 31, v176
	v_add_co_u32_e32 v128, vcc, s21, v170
	v_readlane_b32 s12, v255, 28
	v_lshlrev_b64 v[178:179], 12, v[176:177]
	v_addc_co_u32_e32 v129, vcc, 0, v171, vcc
	v_readlane_b32 s13, v255, 29
	global_load_dwordx4 v[140:143], v[128:129], off
	v_readlane_b32 s68, v252, 0
	v_lshl_add_u64 v[128:129], s[12:13], 0, v[178:179]
	v_lshl_add_u64 v[180:181], v[128:129], 0, v[174:175]
	global_load_dwordx4 v[144:147], v[180:181], off offset:16 nt
	global_load_dwordx4 v[148:151], v[180:181], off nt
	s_mov_b64 s[12:13], 0x2000
	v_lshl_add_u64 v[128:129], v[170:171], 0, s[12:13]
	global_load_dwordx4 v[136:139], v[128:129], off offset:16
	global_load_dwordx4 v[132:135], v[128:129], off offset:512
	global_load_dwordx4 v[162:165], v[180:181], off offset:512 nt
	global_load_dwordx4 v[200:203], v[180:181], off offset:528 nt
	s_nop 0
	global_load_dwordx4 v[128:131], v[128:129], off offset:528
	v_readlane_b32 s70, v252, 2
	v_readlane_b32 s71, v252, 3
	v_readlane_b32 s69, v252, 1
	v_readlane_b32 s72, v252, 4
	v_readlane_b32 s73, v252, 5
	v_readlane_b32 s74, v252, 6
	v_readlane_b32 s75, v252, 7
	s_waitcnt vmcnt(0)
	v_pk_fma_f32 v[118:119], v[118:119], v[138:139], v[146:147]
	v_pk_fma_f32 v[114:115], v[114:115], v[142:143], v[150:151]
	v_pk_fma_f32 v[112:113], v[112:113], v[140:141], v[148:149]
	v_pk_fma_f32 v[116:117], v[116:117], v[136:137], v[144:145]
	v_pk_fma_f32 v[66:67], v[66:67], v[134:135], v[164:165]
	v_pk_fma_f32 v[64:65], v[64:65], v[132:133], v[162:163]
	v_mul_f32_e32 v144, v113, v113
	v_mul_f32_e32 v145, v115, v115
	v_mul_f32_e32 v146, v117, v117
	v_mul_f32_e32 v147, v119, v119
	v_pk_fma_f32 v[70:71], v[70:71], v[130:131], v[202:203]
	v_pk_fma_f32 v[68:69], v[68:69], v[128:129], v[200:201]
	v_mul_f32_e32 v148, v65, v65
	v_mul_f32_e32 v149, v67, v67
	v_fmac_f32_e32 v144, v112, v112
	v_fmac_f32_e32 v145, v114, v114
	v_fmac_f32_e32 v146, v116, v116
	v_fmac_f32_e32 v147, v118, v118
	v_mul_f32_e32 v150, v69, v69
	v_mul_f32_e32 v151, v71, v71
	v_fmac_f32_e32 v148, v64, v64
	v_fmac_f32_e32 v149, v66, v66
	v_add_f32_e32 v144, v144, v145
	v_add_f32_e32 v145, v146, v147
	v_fmac_f32_e32 v150, v68, v68
	v_fmac_f32_e32 v151, v70, v70
	v_add_f32_e32 v146, v148, v149
	v_add_f32_e32 v144, v144, v145
	v_add_f32_e32 v144, v144, v146
	v_add_f32_e32 v145, v150, v151
	v_add_f32_e32 v146, v144, v145
	ds_bpermute_b32 v147, v213, v146
	v_lshl_add_u64 v[144:145], s[70:71], 0, v[178:179]
	v_lshl_add_u64 v[178:179], v[144:145], 0, v[174:175]
	s_waitcnt lgkmcnt(0)
	v_add_f32_e32 v144, v146, v147
	ds_bpermute_b32 v145, v214, v144
	s_and_saveexec_b64 s[12:13], s[4:5]
	s_cbranch_execz .LBB0_1053
	s_waitcnt lgkmcnt(0)
	v_add_f32_e32 v144, v144, v145
	ds_write_b32 v215, v144
.LBB0_1053:
	s_or_b64 exec, exec, s[12:13]
	v_add_co_u32_e32 v162, vcc, 0x10000, v180
	v_lshl_add_u64 v[148:149], v[180:181], 0, s[88:89]
	s_nop 0
	v_addc_co_u32_e32 v163, vcc, 0, v181, vcc
	s_waitcnt lgkmcnt(0)
	global_load_dwordx4 v[144:147], v[162:163], off nt
	s_mov_b64 s[12:13], 0x10200
	global_load_dwordx4 v[148:151], v[148:149], off offset:16 nt
	s_nop 0
	global_load_dwordx4 v[162:165], v[162:163], off offset:512 nt
	v_lshl_add_u64 v[200:201], v[180:181], 0, s[12:13]
	global_load_dwordx4 v[200:203], v[200:201], off offset:16 nt
	s_mov_b32 s12, 0x10000
	s_waitcnt vmcnt(3)
	v_pk_fma_f32 v[122:123], v[122:123], v[142:143], v[146:147]
	v_pk_fma_f32 v[120:121], v[120:121], v[140:141], v[144:145]
	s_waitcnt vmcnt(2)
	v_pk_fma_f32 v[126:127], v[126:127], v[138:139], v[150:151]
	v_pk_fma_f32 v[124:125], v[124:125], v[136:137], v[148:149]
	s_waitcnt vmcnt(1)
	v_pk_fma_f32 v[86:87], v[86:87], v[134:135], v[164:165]
	v_pk_fma_f32 v[84:85], v[84:85], v[132:133], v[162:163]
	v_mul_f32_e32 v144, v121, v121
	v_mul_f32_e32 v145, v123, v123
	v_mul_f32_e32 v146, v125, v125
	v_mul_f32_e32 v147, v127, v127
	s_waitcnt vmcnt(0)
	v_pk_fma_f32 v[94:95], v[94:95], v[130:131], v[202:203]
	v_pk_fma_f32 v[92:93], v[92:93], v[128:129], v[200:201]
	v_mul_f32_e32 v148, v85, v85
	v_mul_f32_e32 v149, v87, v87
	v_fmac_f32_e32 v144, v120, v120
	v_fmac_f32_e32 v145, v122, v122
	v_fmac_f32_e32 v146, v124, v124
	v_fmac_f32_e32 v147, v126, v126
	v_mul_f32_e32 v150, v93, v93
	v_mul_f32_e32 v151, v95, v95
	v_fmac_f32_e32 v148, v84, v84
	v_fmac_f32_e32 v149, v86, v86
	v_add_f32_e32 v144, v144, v145
	v_add_f32_e32 v145, v146, v147
	v_fmac_f32_e32 v150, v92, v92
	v_fmac_f32_e32 v151, v94, v94
	v_add_f32_e32 v146, v148, v149
	v_add_f32_e32 v144, v144, v145
	v_add_f32_e32 v147, v150, v151
	v_add_f32_e32 v144, v144, v146
	v_add_f32_e32 v144, v144, v147
	ds_bpermute_b32 v145, v213, v144
	v_add_co_u32_e32 v216, vcc, s12, v178
	s_waitcnt lgkmcnt(0)
	v_add_f32_e32 v144, v144, v145
	ds_bpermute_b32 v145, v214, v144
	v_addc_co_u32_e32 v217, vcc, 0, v179, vcc
	s_and_saveexec_b64 s[12:13], s[4:5]
	s_cbranch_execz .LBB0_1055
	s_waitcnt lgkmcnt(0)
	v_add_f32_e32 v144, v144, v145
	ds_write_b32 v215, v144 offset:256
; #define LAS __attribute__((address_space(3)))
; #define EF_LOAD(buf, g_) do { const float* xp_ = xi + (size_t)(((g_) >> 2) * 128 + ((g_) & 3) * 16) * DM; \
;             _Pragma("unroll") for (int bj = 0; bj < 2; ++bj) _Pragma("unroll") for (int n = 0; n < 2; ++n) xv[buf][bj][n] = *(const f32x4*)(xp_ + bj * 128 + n * 4); } while (0)
;     __device__ __forceinline__ void fused(Acc& acc, const pg8::Unit& u, int wr, int wc, int fr, int fq, LAS unsigned char* lds, int wid, int lane) const {
;     ...
;         LAS float* P = (LAS float*)lds;
;         LAS float* S = (LAS float*)(lds + 4096);
; #pragma unroll
;         for (int g_ = 0; g_ < 8; ++g_) {
;             EF_LOAD(0, g_);
;             float sq = 0.f;
; #pragma unroll
;             for (int bj = 0; bj < 2; ++bj)
; #pragma unroll
;                 for (int n = 0; n < 2; ++n) { const f32x4 xn = xv[0][bj][n] + gt[bj][n] * acc[g_ >> 2][bj][g_ & 3][n]; acc[g_ >> 2][bj][g_ & 3][n] = xn;
;                     if (MODE == 1) *(f32x4*)(xo + (size_t)((g_ >> 2) * 128 + (g_ & 3) * 16) * DM + bj * 128 + n * 4) = xn;
;                     sq += (xn[0] * xn[0] + xn[1] * xn[1]) + (xn[2] * xn[2] + xn[3] * xn[3]); }
;             sq += __shfl_xor(sq, 16); sq += __shfl_xor(sq, 32);
;             if (fq == 0) P[((g_ >> 2) * 128 + wr * 64 + (g_ & 3) * 16 + fr) * 4 + wc] = sq;
;         }
.LBB0_1055:
	s_or_b64 exec, exec, s[12:13]
	v_add_co_u32_e32 v162, vcc, 0x20000, v180
	s_mov_b64 s[12:13], 0x20000
	s_nop 0
	v_addc_co_u32_e32 v163, vcc, 0, v181, vcc
	s_waitcnt lgkmcnt(0)
	global_load_dwordx4 v[144:147], v[162:163], off nt
	v_lshl_add_u64 v[148:149], v[180:181], 0, s[12:13]
	s_mov_b64 s[12:13], 0x20200
	global_load_dwordx4 v[148:151], v[148:149], off offset:16 nt
	s_nop 0
	global_load_dwordx4 v[162:165], v[162:163], off offset:512 nt
	v_lshl_add_u64 v[200:201], v[180:181], 0, s[12:13]
	global_load_dwordx4 v[200:203], v[200:201], off offset:16 nt
	s_mov_b32 s12, 0x20000
	s_waitcnt vmcnt(3)
	v_pk_fma_f32 v[110:111], v[110:111], v[142:143], v[146:147]
	v_pk_fma_f32 v[108:109], v[108:109], v[140:141], v[144:145]
	s_waitcnt vmcnt(2)
	v_pk_fma_f32 v[106:107], v[106:107], v[138:139], v[150:151]
	v_pk_fma_f32 v[104:105], v[104:105], v[136:137], v[148:149]
	s_waitcnt vmcnt(1)
	v_pk_fma_f32 v[102:103], v[102:103], v[134:135], v[164:165]
	v_pk_fma_f32 v[100:101], v[100:101], v[132:133], v[162:163]
	v_mul_f32_e32 v144, v109, v109
	v_mul_f32_e32 v145, v111, v111
	v_mul_f32_e32 v146, v105, v105
	v_mul_f32_e32 v147, v107, v107
	s_waitcnt vmcnt(0)
	v_pk_fma_f32 v[98:99], v[98:99], v[130:131], v[202:203]
	v_pk_fma_f32 v[96:97], v[96:97], v[128:129], v[200:201]
	v_mul_f32_e32 v148, v101, v101
	v_mul_f32_e32 v149, v103, v103
	v_fmac_f32_e32 v144, v108, v108
	v_fmac_f32_e32 v145, v110, v110
	v_fmac_f32_e32 v146, v104, v104
	v_fmac_f32_e32 v147, v106, v106
	v_mul_f32_e32 v150, v97, v97
	v_mul_f32_e32 v151, v99, v99
	v_fmac_f32_e32 v148, v100, v100
	v_fmac_f32_e32 v149, v102, v102
	v_add_f32_e32 v144, v144, v145
	v_add_f32_e32 v145, v146, v147
	v_fmac_f32_e32 v150, v96, v96
	v_fmac_f32_e32 v151, v98, v98
	v_add_f32_e32 v146, v148, v149
	v_add_f32_e32 v144, v144, v145
	v_add_f32_e32 v147, v150, v151
	v_add_f32_e32 v144, v144, v146
	v_add_f32_e32 v144, v144, v147
	ds_bpermute_b32 v145, v213, v144
	v_add_co_u32_e32 v218, vcc, s12, v178
	s_waitcnt lgkmcnt(0)
	v_add_f32_e32 v144, v144, v145
	ds_bpermute_b32 v145, v214, v144
	v_addc_co_u32_e32 v219, vcc, 0, v179, vcc
	s_and_saveexec_b64 s[12:13], s[4:5]
	v_readlane_b32 s72, v255, 36
	v_readlane_b32 s73, v255, 37
	s_cbranch_execz .LBB0_1057
	s_waitcnt lgkmcnt(0)
	v_add_f32_e32 v144, v144, v145
	ds_write_b32 v215, v144 offset:512
.LBB0_1057:
	s_or_b64 exec, exec, s[12:13]
	v_add_co_u32_e32 v162, vcc, 0x30000, v180
	s_mov_b64 s[12:13], 0x30000
	s_nop 0
	v_addc_co_u32_e32 v163, vcc, 0, v181, vcc
	s_waitcnt lgkmcnt(0)
	global_load_dwordx4 v[144:147], v[162:163], off nt
	v_lshl_add_u64 v[148:149], v[180:181], 0, s[12:13]
	s_mov_b64 s[12:13], 0x30200
	global_load_dwordx4 v[148:151], v[148:149], off offset:16 nt
	s_nop 0
	global_load_dwordx4 v[162:165], v[162:163], off offset:512 nt
	v_lshl_add_u64 v[200:201], v[180:181], 0, s[12:13]
	global_load_dwordx4 v[200:203], v[200:201], off offset:16 nt
	s_mov_b32 s12, 0x30000
	s_waitcnt vmcnt(3)
	v_pk_fma_f32 v[90:91], v[90:91], v[142:143], v[146:147]
	v_pk_fma_f32 v[88:89], v[88:89], v[140:141], v[144:145]
	s_waitcnt vmcnt(2)
	v_pk_fma_f32 v[82:83], v[82:83], v[138:139], v[150:151]
	v_pk_fma_f32 v[80:81], v[80:81], v[136:137], v[148:149]
	s_waitcnt vmcnt(1)
	v_pk_fma_f32 v[78:79], v[78:79], v[134:135], v[164:165]
	v_pk_fma_f32 v[76:77], v[76:77], v[132:133], v[162:163]
	v_mul_f32_e32 v144, v89, v89
	v_mul_f32_e32 v145, v91, v91
	v_mul_f32_e32 v146, v81, v81
	v_mul_f32_e32 v147, v83, v83
	s_waitcnt vmcnt(0)
	v_pk_fma_f32 v[74:75], v[74:75], v[130:131], v[202:203]
	v_pk_fma_f32 v[72:73], v[72:73], v[128:129], v[200:201]
	v_mul_f32_e32 v148, v77, v77
	v_mul_f32_e32 v149, v79, v79
	v_fmac_f32_e32 v144, v88, v88
	v_fmac_f32_e32 v145, v90, v90
	v_fmac_f32_e32 v146, v80, v80
	v_fmac_f32_e32 v147, v82, v82
	v_mul_f32_e32 v150, v73, v73
	v_mul_f32_e32 v151, v75, v75
	v_fmac_f32_e32 v148, v76, v76
	v_fmac_f32_e32 v149, v78, v78
	v_add_f32_e32 v144, v144, v145
	v_add_f32_e32 v145, v146, v147
	v_fmac_f32_e32 v150, v72, v72
	v_fmac_f32_e32 v151, v74, v74
	v_add_f32_e32 v146, v148, v149
	v_add_f32_e32 v144, v144, v145
	v_add_f32_e32 v147, v150, v151
	v_add_f32_e32 v144, v144, v146
	v_add_f32_e32 v144, v144, v147
	ds_bpermute_b32 v145, v213, v144
	v_add_co_u32_e32 v220, vcc, s12, v178
	s_waitcnt lgkmcnt(0)
	v_add_f32_e32 v144, v144, v145
	ds_bpermute_b32 v145, v214, v144
	v_addc_co_u32_e32 v221, vcc, 0, v179, vcc
	s_and_saveexec_b64 s[12:13], s[4:5]
	s_cbranch_execz .LBB0_1059
	s_waitcnt lgkmcnt(0)
	v_add_f32_e32 v144, v144, v145
	ds_write_b32 v215, v144 offset:768
.LBB0_1059:
	s_or_b64 exec, exec, s[12:13]
	v_add_co_u32_e32 v162, vcc, 0x80000, v180
	s_mov_b64 s[12:13], 0x80000
	s_nop 0
	v_addc_co_u32_e32 v163, vcc, 0, v181, vcc
	s_waitcnt lgkmcnt(0)
	global_load_dwordx4 v[144:147], v[162:163], off nt
	v_lshl_add_u64 v[148:149], v[180:181], 0, s[12:13]
	s_mov_b64 s[12:13], 0x80200
	global_load_dwordx4 v[148:151], v[148:149], off offset:16 nt
	s_nop 0
	global_load_dwordx4 v[162:165], v[162:163], off offset:512 nt
	v_lshl_add_u64 v[200:201], v[180:181], 0, s[12:13]
	global_load_dwordx4 v[200:203], v[200:201], off offset:16 nt
	s_mov_b32 s12, 0x80000
	s_waitcnt vmcnt(3)
	v_pk_fma_f32 v[62:63], v[62:63], v[142:143], v[146:147]
	v_pk_fma_f32 v[60:61], v[60:61], v[140:141], v[144:145]
	s_waitcnt vmcnt(2)
	v_pk_fma_f32 v[58:59], v[58:59], v[138:139], v[150:151]
	v_pk_fma_f32 v[56:57], v[56:57], v[136:137], v[148:149]
	s_waitcnt vmcnt(1)
	v_pk_fma_f32 v[54:55], v[54:55], v[134:135], v[164:165]
	v_pk_fma_f32 v[52:53], v[52:53], v[132:133], v[162:163]
	v_mul_f32_e32 v144, v61, v61
	v_mul_f32_e32 v145, v63, v63
	v_mul_f32_e32 v146, v57, v57
	v_mul_f32_e32 v147, v59, v59
	s_waitcnt vmcnt(0)
	v_pk_fma_f32 v[50:51], v[50:51], v[130:131], v[202:203]
	v_pk_fma_f32 v[48:49], v[48:49], v[128:129], v[200:201]
	v_mul_f32_e32 v148, v53, v53
	v_mul_f32_e32 v149, v55, v55
	v_fmac_f32_e32 v144, v60, v60
	v_fmac_f32_e32 v145, v62, v62
	v_fmac_f32_e32 v146, v56, v56
	v_fmac_f32_e32 v147, v58, v58
	v_mul_f32_e32 v150, v49, v49
	v_mul_f32_e32 v151, v51, v51
	v_fmac_f32_e32 v148, v52, v52
	v_fmac_f32_e32 v149, v54, v54
	v_add_f32_e32 v144, v144, v145
	v_add_f32_e32 v145, v146, v147
	v_fmac_f32_e32 v150, v48, v48
	v_fmac_f32_e32 v151, v50, v50
	v_add_f32_e32 v146, v148, v149
	v_add_f32_e32 v144, v144, v145
	v_add_f32_e32 v147, v150, v151
	v_add_f32_e32 v144, v144, v146
	v_add_f32_e32 v144, v144, v147
	ds_bpermute_b32 v145, v213, v144
	v_add_co_u32_e32 v222, vcc, s12, v178
	s_waitcnt lgkmcnt(0)
	v_add_f32_e32 v144, v144, v145
	ds_bpermute_b32 v145, v214, v144
	v_addc_co_u32_e32 v223, vcc, 0, v179, vcc
	s_and_saveexec_b64 s[12:13], s[4:5]
	s_cbranch_execz .LBB0_1061
	s_waitcnt lgkmcnt(0)
	v_add_f32_e32 v144, v144, v145
	ds_write_b32 v187, v144
; #define LAS __attribute__((address_space(3)))
; #define EF_LOAD(buf, g_) do { const float* xp_ = xi + (size_t)(((g_) >> 2) * 128 + ((g_) & 3) * 16) * DM; \
;             _Pragma("unroll") for (int bj = 0; bj < 2; ++bj) _Pragma("unroll") for (int n = 0; n < 2; ++n) xv[buf][bj][n] = *(const f32x4*)(xp_ + bj * 128 + n * 4); } while (0)
;     __device__ __forceinline__ void fused(Acc& acc, const pg8::Unit& u, int wr, int wc, int fr, int fq, LAS unsigned char* lds, int wid, int lane) const {
;     ...
;         LAS float* P = (LAS float*)lds;
;         LAS float* S = (LAS float*)(lds + 4096);
; #pragma unroll
;         for (int g_ = 0; g_ < 8; ++g_) {
;             EF_LOAD(0, g_);
;             float sq = 0.f;
; #pragma unroll
;             for (int bj = 0; bj < 2; ++bj)
; #pragma unroll
;                 for (int n = 0; n < 2; ++n) { const f32x4 xn = xv[0][bj][n] + gt[bj][n] * acc[g_ >> 2][bj][g_ & 3][n]; acc[g_ >> 2][bj][g_ & 3][n] = xn;
;                     if (MODE == 1) *(f32x4*)(xo + (size_t)((g_ >> 2) * 128 + (g_ & 3) * 16) * DM + bj * 128 + n * 4) = xn;
;                     sq += (xn[0] * xn[0] + xn[1] * xn[1]) + (xn[2] * xn[2] + xn[3] * xn[3]); }
;             sq += __shfl_xor(sq, 16); sq += __shfl_xor(sq, 32);
;             if (fq == 0) P[((g_ >> 2) * 128 + wr * 64 + (g_ & 3) * 16 + fr) * 4 + wc] = sq;
;         }
.LBB0_1061:
	s_or_b64 exec, exec, s[12:13]
	v_add_co_u32_e32 v162, vcc, 0x90000, v180
	s_mov_b64 s[12:13], 0x90000
	s_nop 0
	v_addc_co_u32_e32 v163, vcc, 0, v181, vcc
	s_waitcnt lgkmcnt(0)
	global_load_dwordx4 v[144:147], v[162:163], off nt
	v_lshl_add_u64 v[148:149], v[180:181], 0, s[12:13]
	s_mov_b64 s[12:13], 0x90200
	global_load_dwordx4 v[148:151], v[148:149], off offset:16 nt
	s_nop 0
	global_load_dwordx4 v[162:165], v[162:163], off offset:512 nt
	v_lshl_add_u64 v[200:201], v[180:181], 0, s[12:13]
	global_load_dwordx4 v[200:203], v[200:201], off offset:16 nt
	s_mov_b32 s12, 0x90000
	s_waitcnt vmcnt(3)
	v_pk_fma_f32 v[46:47], v[46:47], v[142:143], v[146:147]
	v_pk_fma_f32 v[44:45], v[44:45], v[140:141], v[144:145]
	s_waitcnt vmcnt(2)
	v_pk_fma_f32 v[42:43], v[42:43], v[138:139], v[150:151]
	v_pk_fma_f32 v[40:41], v[40:41], v[136:137], v[148:149]
	s_waitcnt vmcnt(1)
	v_pk_fma_f32 v[38:39], v[38:39], v[134:135], v[164:165]
	v_pk_fma_f32 v[36:37], v[36:37], v[132:133], v[162:163]
	v_mul_f32_e32 v144, v45, v45
	v_mul_f32_e32 v145, v47, v47
	v_mul_f32_e32 v146, v41, v41
	v_mul_f32_e32 v147, v43, v43
	s_waitcnt vmcnt(0)
	v_pk_fma_f32 v[34:35], v[34:35], v[130:131], v[202:203]
	v_pk_fma_f32 v[32:33], v[32:33], v[128:129], v[200:201]
	v_mul_f32_e32 v148, v37, v37
	v_mul_f32_e32 v149, v39, v39
	v_fmac_f32_e32 v144, v44, v44
	v_fmac_f32_e32 v145, v46, v46
	v_fmac_f32_e32 v146, v40, v40
	v_fmac_f32_e32 v147, v42, v42
	v_mul_f32_e32 v150, v33, v33
	v_mul_f32_e32 v151, v35, v35
	v_fmac_f32_e32 v148, v36, v36
	v_fmac_f32_e32 v149, v38, v38
	v_add_f32_e32 v144, v144, v145
	v_add_f32_e32 v145, v146, v147
	v_fmac_f32_e32 v150, v32, v32
	v_fmac_f32_e32 v151, v34, v34
	v_add_f32_e32 v146, v148, v149
	v_add_f32_e32 v144, v144, v145
	v_add_f32_e32 v147, v150, v151
	v_add_f32_e32 v144, v144, v146
	v_add_f32_e32 v144, v144, v147
	ds_bpermute_b32 v145, v213, v144
	v_add_co_u32_e32 v224, vcc, s12, v178
	s_waitcnt lgkmcnt(0)
	v_add_f32_e32 v144, v144, v145
	ds_bpermute_b32 v145, v214, v144
	v_addc_co_u32_e32 v225, vcc, 0, v179, vcc
	s_and_saveexec_b64 s[12:13], s[4:5]
	s_cbranch_execz .LBB0_1063
	s_waitcnt lgkmcnt(0)
	v_add_f32_e32 v144, v144, v145
	ds_write_b32 v188, v144
.LBB0_1063:
	s_or_b64 exec, exec, s[12:13]
	v_add_co_u32_e32 v162, vcc, 0xa0000, v180
	s_mov_b64 s[12:13], 0xa0000
	s_nop 0
	v_addc_co_u32_e32 v163, vcc, 0, v181, vcc
	v_lshl_add_u64 v[148:149], v[180:181], 0, s[12:13]
	s_mov_b64 s[12:13], 0xa0200
	s_waitcnt lgkmcnt(0)
	global_load_dwordx4 v[144:147], v[162:163], off nt
	v_lshl_add_u64 v[200:201], v[180:181], 0, s[12:13]
	global_load_dwordx4 v[148:151], v[148:149], off offset:16 nt
	s_nop 0
	global_load_dwordx4 v[162:165], v[162:163], off offset:512 nt
	s_mov_b32 s12, 0xa0000
	global_load_dwordx4 v[200:203], v[200:201], off offset:16 nt
	s_waitcnt vmcnt(3)
	v_pk_fma_f32 v[146:147], v[30:31], v[142:143], v[146:147]
	v_pk_fma_f32 v[144:145], v[28:29], v[140:141], v[144:145]
	s_waitcnt vmcnt(2)
	v_pk_fma_f32 v[150:151], v[26:27], v[138:139], v[150:151]
	v_pk_fma_f32 v[148:149], v[24:25], v[136:137], v[148:149]
	s_waitcnt vmcnt(1)
	v_pk_fma_f32 v[26:27], v[22:23], v[134:135], v[164:165]
	v_pk_fma_f32 v[24:25], v[20:21], v[132:133], v[162:163]
	s_waitcnt vmcnt(0)
	v_pk_fma_f32 v[30:31], v[18:19], v[130:131], v[202:203]
	v_pk_fma_f32 v[28:29], v[16:17], v[128:129], v[200:201]
	v_mul_f32_e32 v16, v145, v145
	v_mul_f32_e32 v17, v147, v147
	v_mul_f32_e32 v18, v149, v149
	v_mul_f32_e32 v19, v151, v151
	v_mul_f32_e32 v20, v25, v25
	v_mul_f32_e32 v21, v27, v27
	v_fmac_f32_e32 v16, v144, v144
	v_fmac_f32_e32 v17, v146, v146
	v_fmac_f32_e32 v18, v148, v148
	v_fmac_f32_e32 v19, v150, v150
	v_mul_f32_e32 v22, v29, v29
	v_mul_f32_e32 v23, v31, v31
	v_fmac_f32_e32 v20, v24, v24
	v_fmac_f32_e32 v21, v26, v26
	v_add_f32_e32 v16, v16, v17
	v_add_f32_e32 v17, v18, v19
	v_fmac_f32_e32 v22, v28, v28
	v_fmac_f32_e32 v23, v30, v30
	v_add_f32_e32 v18, v20, v21
	v_add_f32_e32 v16, v16, v17
	v_add_f32_e32 v19, v22, v23
	v_add_f32_e32 v16, v16, v18
	v_add_f32_e32 v16, v16, v19
	ds_bpermute_b32 v17, v213, v16
	v_add_co_u32_e32 v226, vcc, s12, v178
	s_waitcnt lgkmcnt(0)
	v_add_f32_e32 v16, v16, v17
	ds_bpermute_b32 v17, v214, v16
	v_addc_co_u32_e32 v227, vcc, 0, v179, vcc
	s_and_saveexec_b64 s[12:13], s[4:5]
	s_cbranch_execz .LBB0_1065
	s_waitcnt lgkmcnt(0)
	v_add_f32_e32 v16, v16, v17
	ds_write_b32 v189, v16
; #define LAS __attribute__((address_space(3)))
; #define EF_LOAD(buf, g_) do { const float* xp_ = xi + (size_t)(((g_) >> 2) * 128 + ((g_) & 3) * 16) * DM; \
;             _Pragma("unroll") for (int bj = 0; bj < 2; ++bj) _Pragma("unroll") for (int n = 0; n < 2; ++n) xv[buf][bj][n] = *(const f32x4*)(xp_ + bj * 128 + n * 4); } while (0)
;     __device__ __forceinline__ void fused(Acc& acc, const pg8::Unit& u, int wr, int wc, int fr, int fq, LAS unsigned char* lds, int wid, int lane) const {
;     ...
;         LAS float* P = (LAS float*)lds;
;         LAS float* S = (LAS float*)(lds + 4096);
; #pragma unroll
;         for (int g_ = 0; g_ < 8; ++g_) {
;             EF_LOAD(0, g_);
;             float sq = 0.f;
; #pragma unroll
;             for (int bj = 0; bj < 2; ++bj)
; #pragma unroll
;                 for (int n = 0; n < 2; ++n) { const f32x4 xn = xv[0][bj][n] + gt[bj][n] * acc[g_ >> 2][bj][g_ & 3][n]; acc[g_ >> 2][bj][g_ & 3][n] = xn;
;                     if (MODE == 1) *(f32x4*)(xo + (size_t)((g_ >> 2) * 128 + (g_ & 3) * 16) * DM + bj * 128 + n * 4) = xn;
;                     sq += (xn[0] * xn[0] + xn[1] * xn[1]) + (xn[2] * xn[2] + xn[3] * xn[3]); }
;             sq += __shfl_xor(sq, 16); sq += __shfl_xor(sq, 32);
;             if (fq == 0) P[((g_ >> 2) * 128 + wr * 64 + (g_ & 3) * 16 + fr) * 4 + wc] = sq;
;         }
.LBB0_1065:
	s_or_b64 exec, exec, s[12:13]
	v_add_co_u32_e32 v162, vcc, 0xb0000, v180
	s_mov_b64 s[12:13], 0xb0000
	s_nop 0
	v_addc_co_u32_e32 v163, vcc, 0, v181, vcc
	s_waitcnt lgkmcnt(0)
	global_load_dwordx4 v[16:19], v[162:163], off nt
	v_lshl_add_u64 v[20:21], v[180:181], 0, s[12:13]
	s_mov_b64 s[12:13], 0xb0200
	global_load_dwordx4 v[20:23], v[20:21], off offset:16 nt
	s_nop 0
	global_load_dwordx4 v[162:165], v[162:163], off offset:512 nt
	v_lshl_add_u64 v[180:181], v[180:181], 0, s[12:13]
	global_load_dwordx4 v[200:203], v[180:181], off offset:16 nt
	s_mov_b32 s12, 0xb0000
	s_waitcnt vmcnt(3)
	v_pk_fma_f32 v[14:15], v[14:15], v[142:143], v[18:19]
	v_pk_fma_f32 v[12:13], v[12:13], v[140:141], v[16:17]
	s_waitcnt vmcnt(2)
	v_pk_fma_f32 v[10:11], v[10:11], v[138:139], v[22:23]
	v_pk_fma_f32 v[8:9], v[8:9], v[136:137], v[20:21]
	s_waitcnt vmcnt(1)
	v_pk_fma_f32 v[2:3], v[2:3], v[134:135], v[164:165]
	v_pk_fma_f32 v[0:1], v[0:1], v[132:133], v[162:163]
	v_mul_f32_e32 v16, v13, v13
	v_mul_f32_e32 v17, v15, v15
	v_mul_f32_e32 v18, v9, v9
	v_mul_f32_e32 v19, v11, v11
	s_waitcnt vmcnt(0)
	v_pk_fma_f32 v[6:7], v[6:7], v[130:131], v[202:203]
	v_pk_fma_f32 v[4:5], v[4:5], v[128:129], v[200:201]
	v_mul_f32_e32 v20, v1, v1
	v_mul_f32_e32 v21, v3, v3
	v_fmac_f32_e32 v16, v12, v12
	v_fmac_f32_e32 v17, v14, v14
	v_fmac_f32_e32 v18, v8, v8
	v_fmac_f32_e32 v19, v10, v10
	v_mul_f32_e32 v22, v5, v5
	v_mul_f32_e32 v23, v7, v7
	v_fmac_f32_e32 v20, v0, v0
	v_fmac_f32_e32 v21, v2, v2
	v_add_f32_e32 v16, v16, v17
	v_add_f32_e32 v17, v18, v19
	v_fmac_f32_e32 v22, v4, v4
	v_fmac_f32_e32 v23, v6, v6
	v_add_f32_e32 v18, v20, v21
	v_add_f32_e32 v16, v16, v17
	v_add_f32_e32 v19, v22, v23
	v_add_f32_e32 v16, v16, v18
	v_add_f32_e32 v16, v16, v19
	ds_bpermute_b32 v17, v213, v16
	v_add_co_u32_e32 v18, vcc, s12, v178
	s_waitcnt lgkmcnt(0)
	v_add_f32_e32 v16, v16, v17
	ds_bpermute_b32 v17, v214, v16
	v_addc_co_u32_e32 v19, vcc, 0, v179, vcc
	global_store_dwordx4 v[178:179], v[112:115], off
	global_store_dwordx4 v[178:179], v[116:119], off offset:16
	global_store_dwordx4 v[178:179], v[64:67], off offset:512
	global_store_dwordx4 v[178:179], v[68:71], off offset:528
	global_store_dwordx4 v[216:217], v[120:123], off
	global_store_dwordx4 v[216:217], v[124:127], off offset:16
	global_store_dwordx4 v[216:217], v[84:87], off offset:512
	global_store_dwordx4 v[216:217], v[92:95], off offset:528
	global_store_dwordx4 v[218:219], v[108:111], off
	global_store_dwordx4 v[218:219], v[104:107], off offset:16
	global_store_dwordx4 v[218:219], v[100:103], off offset:512
	global_store_dwordx4 v[218:219], v[96:99], off offset:528
	global_store_dwordx4 v[220:221], v[88:91], off
	global_store_dwordx4 v[220:221], v[80:83], off offset:16
	global_store_dwordx4 v[220:221], v[76:79], off offset:512
	global_store_dwordx4 v[220:221], v[72:75], off offset:528
	global_store_dwordx4 v[222:223], v[60:63], off
	global_store_dwordx4 v[222:223], v[56:59], off offset:16
	global_store_dwordx4 v[222:223], v[52:55], off offset:512
	global_store_dwordx4 v[222:223], v[48:51], off offset:528
	global_store_dwordx4 v[224:225], v[44:47], off
	global_store_dwordx4 v[224:225], v[40:43], off offset:16
	global_store_dwordx4 v[224:225], v[36:39], off offset:512
	global_store_dwordx4 v[224:225], v[32:35], off offset:528
	global_store_dwordx4 v[226:227], v[144:147], off
	global_store_dwordx4 v[226:227], v[148:151], off offset:16
	global_store_dwordx4 v[226:227], v[24:27], off offset:512
	global_store_dwordx4 v[226:227], v[28:31], off offset:528
	global_store_dwordx4 v[18:19], v[12:15], off
	global_store_dwordx4 v[18:19], v[8:11], off offset:16
	global_store_dwordx4 v[18:19], v[0:3], off offset:512
	global_store_dwordx4 v[18:19], v[4:7], off offset:528
	s_and_saveexec_b64 s[12:13], s[4:5]
	s_cbranch_execz .LBB0_1067
	s_waitcnt lgkmcnt(0)
	v_add_f32_e32 v16, v16, v17
	ds_write_b32 v190, v16

; #define LAS __attribute__((address_space(3)))
; #define EF_LOAD(buf, g_) do { const float* xp_ = xi + (size_t)(((g_) >> 2) * 128 + ((g_) & 3) * 16) * DM; \
;             _Pragma("unroll") for (int bj = 0; bj < 2; ++bj) _Pragma("unroll") for (int n = 0; n < 2; ++n) xv[buf][bj][n] = *(const f32x4*)(xp_ + bj * 128 + n * 4); } while (0)
;     __device__ __forceinline__ void fused(Acc& acc, const pg8::Unit& u, int wr, int wc, int fr, int fq, LAS unsigned char* lds, int wid, int lane) const {
;         const int tile0 = u.pm * 256, colb = u.pn * 256 + wc * 32 + 8 * fq, rloc = wr * 64 + fr;
;         const float* xi = xin + (size_t)(tile0 + rloc) * DM + colb;
;         float* xo = out + (size_t)(tile0 + rloc) * DM + colb;
;         const float* gp = mod + (tile0 >> 11) * 6144 + goff + colb;
;         f32x4 gt[2][2];
; #pragma unroll
;         for (int bj = 0; bj < 2; ++bj)
; #pragma unroll
;             for (int n = 0; n < 2; ++n) gt[bj][n] = *(const f32x4*)(gp + bj * 128 + n * 4);
;         f32x4 xv[1][2][2];
;     ...
;         LAS float* P = (LAS float*)lds;
;         LAS float* S = (LAS float*)(lds + 4096);
; #pragma unroll
;         for (int g_ = 0; g_ < 8; ++g_) {
;             EF_LOAD(0, g_);
;             float sq = 0.f;
; #pragma unroll
;             for (int bj = 0; bj < 2; ++bj)
; #pragma unroll
;                 for (int n = 0; n < 2; ++n) { const f32x4 xn = xv[0][bj][n] + gt[bj][n] * acc[g_ >> 2][bj][g_ & 3][n]; acc[g_ >> 2][bj][g_ & 3][n] = xn;
;                     if (MODE == 1) *(f32x4*)(xo + (size_t)((g_ >> 2) * 128 + (g_ & 3) * 16) * DM + bj * 128 + n * 4) = xn;
;                     sq += (xn[0] * xn[0] + xn[1] * xn[1]) + (xn[2] * xn[2] + xn[3] * xn[3]); }
;             sq += __shfl_xor(sq, 16); sq += __shfl_xor(sq, 32);
;             if (fq == 0) P[((g_ >> 2) * 128 + wr * 64 + (g_ & 3) * 16 + fr) * 4 + wc] = sq;
;         }
.LBB0_1309:
	s_lshl_b32 s0, s40, 5
	s_lshl_b32 s1, s10, 8
	v_lshrrev_b32_e32 v128, 1, v182
	s_lshl_b32 s8, s38, 8
	s_or_b32 s0, s1, s0
	v_and_or_b32 v146, v128, 24, s0
	s_add_i32 s0, s8, s20
	v_or_b32_e32 v132, s0, v183
	s_lshr_b32 s0, s38, 3
	s_mulk_i32 s0, 0x1800
	s_ashr_i32 s1, s0, 31
	s_lshl_b64 s[0:1], s[0:1], 2
	v_ashrrev_i32_e32 v147, 31, v146
	s_add_u32 s0, s48, s0
	v_ashrrev_i32_e32 v133, 31, v132
	s_addc_u32 s1, s49, s1
	v_lshlrev_b64 v[134:135], 2, v[146:147]
	v_readlane_b32 s52, v252, 0
	v_lshl_add_u64 v[136:137], s[0:1], 0, v[134:135]
	s_movk_i32 s0, 0x5000
	v_lshlrev_b64 v[132:133], 12, v[132:133]
	v_readlane_b32 s54, v252, 2
	v_readlane_b32 s55, v252, 3
	v_add_co_u32_e32 v128, vcc, s0, v136
	s_nop 0
	v_lshl_add_u64 v[132:133], s[54:55], 0, v[132:133]
	v_addc_co_u32_e32 v129, vcc, 0, v137, vcc
	v_lshl_add_u64 v[144:145], v[132:133], 0, v[134:135]
	s_waitcnt vmcnt(0)
	s_barrier
	global_load_dwordx4 v[128:131], v[128:129], off
	s_nop 0
	global_load_dwordx4 v[152:155], v[144:145], off offset:16 nt
	global_load_dwordx4 v[156:159], v[144:145], off nt
	s_mov_b64 s[0:1], 0x5000
	v_lshl_add_u64 v[136:137], v[136:137], 0, s[0:1]
	global_load_dwordx4 v[140:143], v[136:137], off offset:16
	global_load_dwordx4 v[132:135], v[136:137], off offset:512
	global_load_dwordx4 v[162:165], v[144:145], off offset:512 nt
	global_load_dwordx4 v[166:169], v[144:145], off offset:528 nt
	s_nop 0
	global_load_dwordx4 v[136:139], v[136:137], off offset:528
	s_lshl_b32 s6, s40, 2
	v_and_b32_e32 v160, 63, v182
	s_add_i32 s9, s6, 0
	v_cmp_gt_u32_e64 s[0:1], 16, v160
	v_lshl_add_u32 v170, v150, 4, s9
	v_readlane_b32 s53, v252, 1
	v_readlane_b32 s56, v252, 4
	v_readlane_b32 s57, v252, 5
	v_readlane_b32 s58, v252, 6
	v_readlane_b32 s59, v252, 7
	s_waitcnt vmcnt(0)
	v_pk_fma_f32 v[122:123], v[122:123], v[142:143], v[154:155]
	v_pk_fma_f32 v[126:127], v[126:127], v[130:131], v[158:159]
	v_pk_fma_f32 v[124:125], v[124:125], v[128:129], v[156:157]
	v_pk_fma_f32 v[148:149], v[120:121], v[140:141], v[152:153]
	v_pk_fma_f32 v[118:119], v[118:119], v[134:135], v[164:165]
	v_pk_fma_f32 v[116:117], v[116:117], v[132:133], v[162:163]
	v_mul_f32_e32 v120, v125, v125
	v_mul_f32_e32 v121, v127, v127
	v_mul_f32_e32 v151, v149, v149
	v_mul_f32_e32 v152, v123, v123
	v_pk_fma_f32 v[114:115], v[114:115], v[138:139], v[168:169]
	v_pk_fma_f32 v[112:113], v[112:113], v[136:137], v[166:167]
	v_mul_f32_e32 v153, v117, v117
	v_mul_f32_e32 v154, v119, v119
	v_fmac_f32_e32 v120, v124, v124
	v_fmac_f32_e32 v121, v126, v126
	v_fmac_f32_e32 v151, v148, v148
	v_fmac_f32_e32 v152, v122, v122
	v_mul_f32_e32 v155, v113, v113
	v_mul_f32_e32 v156, v115, v115
	v_fmac_f32_e32 v153, v116, v116
	v_fmac_f32_e32 v154, v118, v118
	v_add_f32_e32 v120, v120, v121
	v_add_f32_e32 v121, v151, v152
	v_fmac_f32_e32 v155, v112, v112
	v_fmac_f32_e32 v156, v114, v114
	v_add_f32_e32 v151, v153, v154
	v_add_f32_e32 v120, v120, v121
	v_add_f32_e32 v120, v120, v151
	v_add_f32_e32 v121, v155, v156
	v_add_f32_e32 v120, v120, v121
	ds_bpermute_b32 v121, v213, v120
	s_waitcnt lgkmcnt(0)
	v_add_f32_e32 v120, v120, v121
	ds_bpermute_b32 v121, v214, v120
	s_and_saveexec_b64 s[6:7], s[0:1]
	s_cbranch_execz .LBB0_1311
	s_waitcnt lgkmcnt(0)
	v_add_f32_e32 v120, v120, v121
	ds_write_b32 v170, v120
.LBB0_1311:
	s_or_b64 exec, exec, s[6:7]
	v_add_co_u32_e32 v166, vcc, 0x10000, v144
	v_lshl_add_u64 v[150:151], v[144:145], 0, s[88:89]
	s_mov_b64 s[6:7], 0x10200
	v_addc_co_u32_e32 v167, vcc, 0, v145, vcc
	s_waitcnt lgkmcnt(0)
	v_lshl_add_u64 v[120:121], v[144:145], 0, s[6:7]
	global_load_dwordx4 v[152:155], v[150:151], off offset:16 nt
	global_load_dwordx4 v[156:159], v[120:121], off offset:16 nt
	global_load_dwordx4 v[162:165], v[166:167], off nt
	s_nop 0
	global_load_dwordx4 v[166:169], v[166:167], off offset:512 nt
	s_waitcnt vmcnt(3)
	v_pk_fma_f32 v[110:111], v[110:111], v[142:143], v[154:155]
	v_pk_fma_f32 v[108:109], v[108:109], v[140:141], v[152:153]
	s_waitcnt vmcnt(1)
	v_pk_fma_f32 v[152:153], v[106:107], v[130:131], v[164:165]
	v_pk_fma_f32 v[154:155], v[104:105], v[128:129], v[162:163]
	v_pk_fma_f32 v[100:101], v[100:101], v[136:137], v[156:157]
	v_mul_f32_e32 v106, v109, v109
	v_mul_f32_e32 v107, v111, v111
	s_waitcnt vmcnt(0)
	v_pk_fma_f32 v[98:99], v[98:99], v[134:135], v[168:169]
	v_pk_fma_f32 v[104:105], v[96:97], v[132:133], v[166:167]
	v_mul_f32_e32 v156, v155, v155
	v_mul_f32_e32 v157, v153, v153
	v_pk_fma_f32 v[102:103], v[102:103], v[138:139], v[158:159]
	v_fmac_f32_e32 v106, v108, v108
	v_fmac_f32_e32 v107, v110, v110
	v_mul_f32_e32 v158, v105, v105
	v_mul_f32_e32 v159, v99, v99
	v_fmac_f32_e32 v156, v154, v154
	v_fmac_f32_e32 v157, v152, v152
	v_mul_f32_e32 v96, v101, v101
	v_mul_f32_e32 v97, v103, v103
	v_add_f32_e32 v106, v106, v107
	v_fmac_f32_e32 v158, v104, v104
	v_fmac_f32_e32 v159, v98, v98
	v_add_f32_e32 v107, v156, v157
	v_fmac_f32_e32 v96, v100, v100
	v_fmac_f32_e32 v97, v102, v102
	v_add_f32_e32 v156, v158, v159
	v_add_f32_e32 v106, v107, v106
	v_add_f32_e32 v106, v106, v156
	v_add_f32_e32 v96, v96, v97
	v_add_f32_e32 v96, v106, v96
	ds_bpermute_b32 v97, v213, v96
	s_waitcnt lgkmcnt(0)
	v_add_f32_e32 v96, v96, v97
	ds_bpermute_b32 v97, v214, v96
	s_and_saveexec_b64 s[6:7], s[0:1]
	s_cbranch_execz .LBB0_1313
	s_waitcnt lgkmcnt(0)
	v_add_f32_e32 v96, v96, v97
	ds_write_b32 v170, v96 offset:256
; #define LAS __attribute__((address_space(3)))
; #define EF_LOAD(buf, g_) do { const float* xp_ = xi + (size_t)(((g_) >> 2) * 128 + ((g_) & 3) * 16) * DM; \
;             _Pragma("unroll") for (int bj = 0; bj < 2; ++bj) _Pragma("unroll") for (int n = 0; n < 2; ++n) xv[buf][bj][n] = *(const f32x4*)(xp_ + bj * 128 + n * 4); } while (0)
;     __device__ __forceinline__ void fused(Acc& acc, const pg8::Unit& u, int wr, int wc, int fr, int fq, LAS unsigned char* lds, int wid, int lane) const {
;     ...
;         LAS float* P = (LAS float*)lds;
;         LAS float* S = (LAS float*)(lds + 4096);
; #pragma unroll
;         for (int g_ = 0; g_ < 8; ++g_) {
;             EF_LOAD(0, g_);
;             float sq = 0.f;
; #pragma unroll
;             for (int bj = 0; bj < 2; ++bj)
; #pragma unroll
;                 for (int n = 0; n < 2; ++n) { const f32x4 xn = xv[0][bj][n] + gt[bj][n] * acc[g_ >> 2][bj][g_ & 3][n]; acc[g_ >> 2][bj][g_ & 3][n] = xn;
;                     if (MODE == 1) *(f32x4*)(xo + (size_t)((g_ >> 2) * 128 + (g_ & 3) * 16) * DM + bj * 128 + n * 4) = xn;
;                     sq += (xn[0] * xn[0] + xn[1] * xn[1]) + (xn[2] * xn[2] + xn[3] * xn[3]); }
;             sq += __shfl_xor(sq, 16); sq += __shfl_xor(sq, 32);
;             if (fq == 0) P[((g_ >> 2) * 128 + wr * 64 + (g_ & 3) * 16 + fr) * 4 + wc] = sq;
;         }
.LBB0_1313:
	s_or_b64 exec, exec, s[6:7]
	s_mov_b64 s[6:7], 0x20000
	v_add_co_u32_e32 v172, vcc, 0x20000, v144
	v_lshl_add_u64 v[106:107], v[144:145], 0, s[6:7]
	s_mov_b64 s[6:7], 0x20200
	v_addc_co_u32_e32 v173, vcc, 0, v145, vcc
	s_waitcnt lgkmcnt(0)
	v_lshl_add_u64 v[96:97], v[144:145], 0, s[6:7]
	global_load_dwordx4 v[156:159], v[106:107], off offset:16 nt
	global_load_dwordx4 v[162:165], v[96:97], off offset:16 nt
	global_load_dwordx4 v[166:169], v[172:173], off nt
	s_nop 0
	global_load_dwordx4 v[172:175], v[172:173], off offset:512 nt
	s_waitcnt vmcnt(3)
	v_pk_fma_f32 v[94:95], v[94:95], v[142:143], v[158:159]
	v_pk_fma_f32 v[92:93], v[92:93], v[140:141], v[156:157]
	s_waitcnt vmcnt(1)
	v_pk_fma_f32 v[156:157], v[90:91], v[130:131], v[168:169]
	v_pk_fma_f32 v[158:159], v[88:89], v[128:129], v[166:167]
	v_pk_fma_f32 v[84:85], v[84:85], v[136:137], v[162:163]
	v_mul_f32_e32 v90, v93, v93
	v_mul_f32_e32 v91, v95, v95
	s_waitcnt vmcnt(0)
	v_pk_fma_f32 v[82:83], v[82:83], v[134:135], v[174:175]
	v_pk_fma_f32 v[88:89], v[80:81], v[132:133], v[172:173]
	v_mul_f32_e32 v162, v159, v159
	v_mul_f32_e32 v163, v157, v157
	v_pk_fma_f32 v[86:87], v[86:87], v[138:139], v[164:165]
	v_fmac_f32_e32 v90, v92, v92
	v_fmac_f32_e32 v91, v94, v94
	v_mul_f32_e32 v164, v89, v89
	v_mul_f32_e32 v165, v83, v83
	v_fmac_f32_e32 v162, v158, v158
	v_fmac_f32_e32 v163, v156, v156
	v_mul_f32_e32 v80, v85, v85
	v_mul_f32_e32 v81, v87, v87
	v_add_f32_e32 v90, v90, v91
	v_fmac_f32_e32 v164, v88, v88
	v_fmac_f32_e32 v165, v82, v82
	v_add_f32_e32 v91, v162, v163
	v_fmac_f32_e32 v80, v84, v84
	v_fmac_f32_e32 v81, v86, v86
	v_add_f32_e32 v162, v164, v165
	v_add_f32_e32 v90, v91, v90
	v_add_f32_e32 v90, v90, v162
	v_add_f32_e32 v80, v80, v81
	v_add_f32_e32 v80, v90, v80
	ds_bpermute_b32 v81, v213, v80
	s_waitcnt lgkmcnt(0)
	v_add_f32_e32 v80, v80, v81
	ds_bpermute_b32 v81, v214, v80
	s_and_saveexec_b64 s[6:7], s[0:1]
	s_cbranch_execz .LBB0_1315
	s_waitcnt lgkmcnt(0)
	v_add_f32_e32 v80, v80, v81
	ds_write_b32 v170, v80 offset:512
.LBB0_1315:
	s_or_b64 exec, exec, s[6:7]
	s_mov_b64 s[6:7], 0x30000
	v_lshl_add_u64 v[90:91], v[144:145], 0, s[6:7]
	v_add_co_u32_e32 v176, vcc, 0x30000, v144
	s_mov_b64 s[6:7], 0x30200
	s_waitcnt lgkmcnt(0)
	v_lshl_add_u64 v[80:81], v[144:145], 0, s[6:7]
	global_load_dwordx4 v[162:165], v[90:91], off offset:16 nt
	global_load_dwordx4 v[166:169], v[80:81], off offset:16 nt
	v_addc_co_u32_e32 v177, vcc, 0, v145, vcc
	global_load_dwordx4 v[172:175], v[176:177], off nt
	s_nop 0
	global_load_dwordx4 v[176:179], v[176:177], off offset:512 nt
	s_waitcnt vmcnt(3)
	v_pk_fma_f32 v[78:79], v[78:79], v[142:143], v[164:165]
	v_pk_fma_f32 v[76:77], v[76:77], v[140:141], v[162:163]
	s_waitcnt vmcnt(2)
	v_pk_fma_f32 v[70:71], v[70:71], v[138:139], v[168:169]
	v_pk_fma_f32 v[68:69], v[68:69], v[136:137], v[166:167]
	s_waitcnt vmcnt(1)
	v_pk_fma_f32 v[166:167], v[74:75], v[130:131], v[174:175]
	v_pk_fma_f32 v[168:169], v[72:73], v[128:129], v[172:173]
	v_mul_f32_e32 v74, v77, v77
	v_mul_f32_e32 v75, v79, v79
	s_waitcnt vmcnt(0)
	v_pk_fma_f32 v[66:67], v[66:67], v[134:135], v[178:179]
	v_pk_fma_f32 v[72:73], v[64:65], v[132:133], v[176:177]
	v_mul_f32_e32 v162, v169, v169
	v_mul_f32_e32 v163, v167, v167
	v_fmac_f32_e32 v74, v76, v76
	v_fmac_f32_e32 v75, v78, v78
	v_mul_f32_e32 v164, v73, v73
	v_mul_f32_e32 v165, v67, v67
	v_fmac_f32_e32 v162, v168, v168
	v_fmac_f32_e32 v163, v166, v166
	v_mul_f32_e32 v64, v69, v69
	v_mul_f32_e32 v65, v71, v71
	v_add_f32_e32 v74, v74, v75
	v_fmac_f32_e32 v164, v72, v72
	v_fmac_f32_e32 v165, v66, v66
	v_add_f32_e32 v75, v162, v163
	v_fmac_f32_e32 v64, v68, v68
	v_fmac_f32_e32 v65, v70, v70
	v_add_f32_e32 v162, v164, v165
	v_add_f32_e32 v74, v75, v74
	v_add_f32_e32 v74, v74, v162
	v_add_f32_e32 v64, v64, v65
	v_add_f32_e32 v64, v74, v64
	ds_bpermute_b32 v65, v213, v64
	s_waitcnt lgkmcnt(0)
	v_add_f32_e32 v64, v64, v65
	ds_bpermute_b32 v65, v214, v64
	s_and_saveexec_b64 s[6:7], s[0:1]
	s_cbranch_execz .LBB0_1317
	s_waitcnt lgkmcnt(0)
	v_add_f32_e32 v64, v64, v65
	ds_write_b32 v170, v64 offset:768
.LBB0_1317:
	s_or_b64 exec, exec, s[6:7]
	s_mov_b64 s[6:7], 0x80000
	v_add_co_u32_e32 v174, vcc, 0x80000, v144
	v_lshl_add_u64 v[74:75], v[144:145], 0, s[6:7]
	s_mov_b64 s[6:7], 0x80200
	v_addc_co_u32_e32 v175, vcc, 0, v145, vcc
	s_waitcnt lgkmcnt(0)
	v_lshl_add_u64 v[64:65], v[144:145], 0, s[6:7]
	global_load_dwordx4 v[162:165], v[74:75], off offset:16 nt
	global_load_dwordx4 v[170:173], v[64:65], off offset:16 nt
	global_load_dwordx4 v[184:187], v[174:175], off nt
	global_load_dwordx4 v[188:191], v[174:175], off offset:512 nt
	s_waitcnt vmcnt(3)
	v_pk_fma_f32 v[174:175], v[62:63], v[142:143], v[164:165]
	v_pk_fma_f32 v[176:177], v[60:61], v[140:141], v[162:163]
	s_waitcnt vmcnt(1)
	v_pk_fma_f32 v[178:179], v[58:59], v[130:131], v[186:187]
	v_pk_fma_f32 v[180:181], v[56:57], v[128:129], v[184:185]
	v_mul_f32_e32 v56, v177, v177
	v_mul_f32_e32 v57, v175, v175
	s_waitcnt vmcnt(0)
	v_pk_fma_f32 v[50:51], v[50:51], v[134:135], v[190:191]
	v_pk_fma_f32 v[48:49], v[48:49], v[132:133], v[188:189]
	v_mul_f32_e32 v60, v181, v181
	v_mul_f32_e32 v61, v179, v179
	v_pk_fma_f32 v[54:55], v[54:55], v[138:139], v[172:173]
	v_pk_fma_f32 v[52:53], v[52:53], v[136:137], v[170:171]
	v_fmac_f32_e32 v56, v176, v176
	v_fmac_f32_e32 v57, v174, v174
	v_mul_f32_e32 v62, v49, v49
	v_mul_f32_e32 v63, v51, v51
	v_fmac_f32_e32 v60, v180, v180
	v_fmac_f32_e32 v61, v178, v178
	v_mul_f32_e32 v58, v53, v53
	v_mul_f32_e32 v59, v55, v55
	v_add_f32_e32 v56, v56, v57
	v_fmac_f32_e32 v62, v48, v48
	v_fmac_f32_e32 v63, v50, v50
	v_add_f32_e32 v57, v60, v61
	v_fmac_f32_e32 v58, v52, v52
	v_fmac_f32_e32 v59, v54, v54
	v_add_f32_e32 v60, v62, v63
	v_add_f32_e32 v56, v57, v56
	v_add_f32_e32 v56, v56, v60
	v_add_f32_e32 v57, v58, v59
	v_add_f32_e32 v56, v56, v57
	ds_bpermute_b32 v57, v213, v56
	s_waitcnt lgkmcnt(0)
	v_add_f32_e32 v56, v56, v57
	ds_bpermute_b32 v57, v214, v56
	s_and_saveexec_b64 s[6:7], s[0:1]
	s_cbranch_execz .LBB0_1319
	s_add_i32 s12, s20, 0x80
	v_or_b32_e32 v58, s12, v183
	v_lshl_add_u32 v58, v58, 4, s9
	s_waitcnt lgkmcnt(0)
	v_add_f32_e32 v56, v56, v57
	ds_write_b32 v58, v56
; #define LAS __attribute__((address_space(3)))
; #define EF_LOAD(buf, g_) do { const float* xp_ = xi + (size_t)(((g_) >> 2) * 128 + ((g_) & 3) * 16) * DM; \
;             _Pragma("unroll") for (int bj = 0; bj < 2; ++bj) _Pragma("unroll") for (int n = 0; n < 2; ++n) xv[buf][bj][n] = *(const f32x4*)(xp_ + bj * 128 + n * 4); } while (0)
;     __device__ __forceinline__ void fused(Acc& acc, const pg8::Unit& u, int wr, int wc, int fr, int fq, LAS unsigned char* lds, int wid, int lane) const {
;     ...
;         LAS float* P = (LAS float*)lds;
;         LAS float* S = (LAS float*)(lds + 4096);
; #pragma unroll
;         for (int g_ = 0; g_ < 8; ++g_) {
;             EF_LOAD(0, g_);
;             float sq = 0.f;
; #pragma unroll
;             for (int bj = 0; bj < 2; ++bj)
; #pragma unroll
;                 for (int n = 0; n < 2; ++n) { const f32x4 xn = xv[0][bj][n] + gt[bj][n] * acc[g_ >> 2][bj][g_ & 3][n]; acc[g_ >> 2][bj][g_ & 3][n] = xn;
;                     if (MODE == 1) *(f32x4*)(xo + (size_t)((g_ >> 2) * 128 + (g_ & 3) * 16) * DM + bj * 128 + n * 4) = xn;
;                     sq += (xn[0] * xn[0] + xn[1] * xn[1]) + (xn[2] * xn[2] + xn[3] * xn[3]); }
;             sq += __shfl_xor(sq, 16); sq += __shfl_xor(sq, 32);
;             if (fq == 0) P[((g_ >> 2) * 128 + wr * 64 + (g_ & 3) * 16 + fr) * 4 + wc] = sq;
;         }
.LBB0_1319:
	s_or_b64 exec, exec, s[6:7]
	s_mov_b64 s[6:7], 0x90000
	v_add_co_u32_e32 v170, vcc, 0x90000, v144
	v_lshl_add_u64 v[58:59], v[144:145], 0, s[6:7]
	s_mov_b64 s[6:7], 0x90200
	v_addc_co_u32_e32 v171, vcc, 0, v145, vcc
	s_waitcnt lgkmcnt(0)
	v_lshl_add_u64 v[56:57], v[144:145], 0, s[6:7]
	global_load_dwordx4 v[60:63], v[58:59], off offset:16 nt
	global_load_dwordx4 v[162:165], v[56:57], off offset:16 nt
	global_load_dwordx4 v[184:187], v[170:171], off nt
	global_load_dwordx4 v[188:191], v[170:171], off offset:512 nt
	s_waitcnt vmcnt(3)
	v_pk_fma_f32 v[46:47], v[46:47], v[142:143], v[62:63]
	v_pk_fma_f32 v[44:45], v[44:45], v[140:141], v[60:61]
	s_waitcnt vmcnt(1)
	v_pk_fma_f32 v[170:171], v[42:43], v[130:131], v[186:187]
	v_pk_fma_f32 v[60:61], v[40:41], v[128:129], v[184:185]
	v_mul_f32_e32 v40, v45, v45
	v_mul_f32_e32 v41, v47, v47
	s_waitcnt vmcnt(0)
	v_pk_fma_f32 v[34:35], v[34:35], v[134:135], v[190:191]
	v_pk_fma_f32 v[32:33], v[32:33], v[132:133], v[188:189]
	v_mul_f32_e32 v62, v61, v61
	v_mul_f32_e32 v63, v171, v171
	v_pk_fma_f32 v[38:39], v[38:39], v[138:139], v[164:165]
	v_pk_fma_f32 v[36:37], v[36:37], v[136:137], v[162:163]
	v_fmac_f32_e32 v40, v44, v44
	v_fmac_f32_e32 v41, v46, v46
	v_mul_f32_e32 v162, v33, v33
	v_mul_f32_e32 v163, v35, v35
	v_fmac_f32_e32 v62, v60, v60
	v_fmac_f32_e32 v63, v170, v170
	v_mul_f32_e32 v42, v37, v37
	v_mul_f32_e32 v43, v39, v39
	v_add_f32_e32 v40, v40, v41
	v_fmac_f32_e32 v162, v32, v32
	v_fmac_f32_e32 v163, v34, v34
	v_add_f32_e32 v41, v62, v63
	v_fmac_f32_e32 v42, v36, v36
	v_fmac_f32_e32 v43, v38, v38
	v_add_f32_e32 v62, v162, v163
	v_add_f32_e32 v40, v41, v40
	v_add_f32_e32 v40, v40, v62
	v_add_f32_e32 v41, v42, v43
	v_add_f32_e32 v40, v40, v41
	ds_bpermute_b32 v41, v213, v40
	s_waitcnt lgkmcnt(0)
	v_add_f32_e32 v40, v40, v41
	ds_bpermute_b32 v41, v214, v40
	s_and_saveexec_b64 s[6:7], s[0:1]
	s_cbranch_execz .LBB0_1321
	s_add_i32 s12, s20, 0x90
	v_or_b32_e32 v42, s12, v183
	v_lshl_add_u32 v42, v42, 4, s9
	s_waitcnt lgkmcnt(0)
	v_add_f32_e32 v40, v40, v41
	ds_write_b32 v42, v40
.LBB0_1321:
	s_or_b64 exec, exec, s[6:7]
	s_mov_b64 s[6:7], 0xa0000
	v_add_co_u32_e32 v62, vcc, 0xa0000, v144
	v_lshl_add_u64 v[42:43], v[144:145], 0, s[6:7]
	s_mov_b64 s[6:7], 0xa0200
	v_addc_co_u32_e32 v63, vcc, 0, v145, vcc
	s_waitcnt lgkmcnt(0)
	v_lshl_add_u64 v[40:41], v[144:145], 0, s[6:7]
	global_load_dwordx4 v[162:165], v[42:43], off offset:16 nt
	global_load_dwordx4 v[184:187], v[40:41], off offset:16 nt
	global_load_dwordx4 v[188:191], v[62:63], off nt
	global_load_dwordx4 v[200:203], v[62:63], off offset:512 nt
	s_waitcnt vmcnt(3)
	v_pk_fma_f32 v[30:31], v[30:31], v[142:143], v[164:165]
	v_pk_fma_f32 v[28:29], v[28:29], v[140:141], v[162:163]
	s_waitcnt vmcnt(1)
	v_pk_fma_f32 v[26:27], v[26:27], v[130:131], v[190:191]
	v_pk_fma_f32 v[62:63], v[24:25], v[128:129], v[188:189]
	v_mul_f32_e32 v24, v29, v29
	v_mul_f32_e32 v25, v31, v31
	s_waitcnt vmcnt(0)
	v_pk_fma_f32 v[18:19], v[18:19], v[134:135], v[202:203]
	v_pk_fma_f32 v[16:17], v[16:17], v[132:133], v[200:201]
	v_mul_f32_e32 v164, v63, v63
	v_mul_f32_e32 v165, v27, v27
	v_pk_fma_f32 v[22:23], v[22:23], v[138:139], v[186:187]
	v_pk_fma_f32 v[20:21], v[20:21], v[136:137], v[184:185]
	v_fmac_f32_e32 v24, v28, v28
	v_fmac_f32_e32 v25, v30, v30
	v_mul_f32_e32 v172, v17, v17
	v_mul_f32_e32 v173, v19, v19
	v_fmac_f32_e32 v164, v62, v62
	v_fmac_f32_e32 v165, v26, v26
	v_mul_f32_e32 v162, v21, v21
	v_mul_f32_e32 v163, v23, v23
	v_add_f32_e32 v24, v24, v25
	v_fmac_f32_e32 v172, v16, v16
	v_fmac_f32_e32 v173, v18, v18
	v_add_f32_e32 v25, v164, v165
	v_fmac_f32_e32 v162, v20, v20
	v_fmac_f32_e32 v163, v22, v22
	v_add_f32_e32 v164, v172, v173
	v_add_f32_e32 v24, v25, v24
	v_add_f32_e32 v24, v24, v164
	v_add_f32_e32 v25, v162, v163
	v_add_f32_e32 v24, v24, v25
	ds_bpermute_b32 v25, v213, v24
	s_waitcnt lgkmcnt(0)
	v_add_f32_e32 v24, v24, v25
	ds_bpermute_b32 v25, v214, v24
	s_and_saveexec_b64 s[6:7], s[0:1]
	s_cbranch_execz .LBB0_1323
	s_add_i32 s12, s20, 0xa0
	v_or_b32_e32 v162, s12, v183
	v_lshl_add_u32 v162, v162, 4, s9
	s_waitcnt lgkmcnt(0)
	v_add_f32_e32 v24, v24, v25
	ds_write_b32 v162, v24
.LBB0_1323:
	s_or_b64 exec, exec, s[6:7]
	s_mov_b64 s[6:7], 0xb0000
	v_add_co_u32_e32 v200, vcc, 0xb0000, v144
	v_lshl_add_u64 v[172:173], v[144:145], 0, s[6:7]
	s_mov_b64 s[6:7], 0xb0200
	v_addc_co_u32_e32 v201, vcc, 0, v145, vcc
	s_waitcnt lgkmcnt(0)
	v_lshl_add_u64 v[24:25], v[144:145], 0, s[6:7]
	global_load_dwordx4 v[162:165], v[172:173], off offset:16 nt
	global_load_dwordx4 v[184:187], v[24:25], off offset:16 nt
	global_load_dwordx4 v[188:191], v[200:201], off nt
	s_nop 0
	global_load_dwordx4 v[200:203], v[200:201], off offset:512 nt
	s_waitcnt vmcnt(3)
	v_pk_fma_f32 v[142:143], v[14:15], v[142:143], v[164:165]
	v_pk_fma_f32 v[140:141], v[12:13], v[140:141], v[162:163]
	s_waitcnt vmcnt(1)
	v_pk_fma_f32 v[130:131], v[10:11], v[130:131], v[190:191]
	v_pk_fma_f32 v[128:129], v[8:9], v[128:129], v[188:189]
	v_pk_fma_f32 v[14:15], v[0:1], v[136:137], v[184:185]
	v_mul_f32_e32 v0, v141, v141
	v_mul_f32_e32 v1, v143, v143
	s_waitcnt vmcnt(0)
	v_pk_fma_f32 v[8:9], v[6:7], v[134:135], v[202:203]
	v_pk_fma_f32 v[10:11], v[4:5], v[132:133], v[200:201]
	v_mul_f32_e32 v4, v129, v129
	v_mul_f32_e32 v5, v131, v131
	v_pk_fma_f32 v[12:13], v[2:3], v[138:139], v[186:187]
	v_fmac_f32_e32 v0, v140, v140
	v_fmac_f32_e32 v1, v142, v142
	v_mul_f32_e32 v6, v11, v11
	v_mul_f32_e32 v7, v9, v9
	v_fmac_f32_e32 v4, v128, v128
	v_fmac_f32_e32 v5, v130, v130
	v_mul_f32_e32 v2, v15, v15
	v_mul_f32_e32 v3, v13, v13
	v_add_f32_e32 v0, v0, v1
	v_fmac_f32_e32 v6, v10, v10
	v_fmac_f32_e32 v7, v8, v8
	v_add_f32_e32 v1, v4, v5
	v_fmac_f32_e32 v2, v14, v14
	v_fmac_f32_e32 v3, v12, v12
	v_add_f32_e32 v4, v6, v7
	v_add_f32_e32 v0, v1, v0
	v_add_f32_e32 v0, v0, v4
	v_add_f32_e32 v1, v2, v3
	v_add_f32_e32 v0, v0, v1
	ds_bpermute_b32 v1, v213, v0
	s_waitcnt lgkmcnt(0)
	v_add_f32_e32 v0, v0, v1
	ds_bpermute_b32 v1, v214, v0
	s_and_saveexec_b64 s[6:7], s[0:1]
	s_cbranch_execz .LBB0_1325
	s_add_i32 s0, s20, 0xb0
	v_or_b32_e32 v2, s0, v183
	v_lshl_add_u32 v2, v2, 4, s9
	s_waitcnt lgkmcnt(0)
	v_add_f32_e32 v0, v0, v1
	ds_write_b32 v2, v0

; #define LAS __attribute__((address_space(3)))
; #define EF_LOAD(buf, g_) do { const float* xp_ = xi + (size_t)(((g_) >> 2) * 128 + ((g_) & 3) * 16) * DM; \
;             _Pragma("unroll") for (int bj = 0; bj < 2; ++bj) _Pragma("unroll") for (int n = 0; n < 2; ++n) xv[buf][bj][n] = *(const f32x4*)(xp_ + bj * 128 + n * 4); } while (0)
;     __device__ __forceinline__ void fused(Acc& acc, const pg8::Unit& u, int wr, int wc, int fr, int fq, LAS unsigned char* lds, int wid, int lane) const {
;         const int tile0 = u.pm * 256, colb = u.pn * 256 + wc * 32 + 8 * fq, rloc = wr * 64 + fr;
;         const float* xi = xin + (size_t)(tile0 + rloc) * DM + colb;
;         float* xo = out + (size_t)(tile0 + rloc) * DM + colb;
;         const float* gp = mod + (tile0 >> 11) * 6144 + goff + colb;
;         f32x4 gt[2][2];
; #pragma unroll
;         for (int bj = 0; bj < 2; ++bj)
; #pragma unroll
;             for (int n = 0; n < 2; ++n) gt[bj][n] = *(const f32x4*)(gp + bj * 128 + n * 4);
;         f32x4 xv[1][2][2];
;     ...
;         LAS float* P = (LAS float*)lds;
;         LAS float* S = (LAS float*)(lds + 4096);
; #pragma unroll
;         for (int g_ = 0; g_ < 8; ++g_) {
;             EF_LOAD(0, g_);
;             float sq = 0.f;
; #pragma unroll
;             for (int bj = 0; bj < 2; ++bj)
; #pragma unroll
;                 for (int n = 0; n < 2; ++n) { const f32x4 xn = xv[0][bj][n] + gt[bj][n] * acc[g_ >> 2][bj][g_ & 3][n]; acc[g_ >> 2][bj][g_ & 3][n] = xn;
;                     if (MODE == 1) *(f32x4*)(xo + (size_t)((g_ >> 2) * 128 + (g_ & 3) * 16) * DM + bj * 128 + n * 4) = xn;
;                     sq += (xn[0] * xn[0] + xn[1] * xn[1]) + (xn[2] * xn[2] + xn[3] * xn[3]); }
;             sq += __shfl_xor(sq, 16); sq += __shfl_xor(sq, 32);
;             if (fq == 0) P[((g_ >> 2) * 128 + wr * 64 + (g_ & 3) * 16 + fr) * 4 + wc] = sq;
;         }
.LBB0_1413:
	s_lshr_b32 s12, s93, 3
	s_mulk_i32 s12, 0x1800
	s_ashr_i32 s13, s12, 31
	s_lshl_b64 s[90:91], s[12:13], 2
	v_add_u32_e32 v172, s34, v158
	s_add_u32 s12, s48, s90
	v_ashrrev_i32_e32 v173, 31, v172
	v_readlane_b32 s68, v252, 0
	s_addc_u32 s13, s49, s91
	v_lshlrev_b64 v[174:175], 2, v[170:171]
	v_lshlrev_b64 v[128:129], 12, v[172:173]
	v_readlane_b32 s70, v252, 2
	v_readlane_b32 s71, v252, 3
	v_lshl_add_u64 v[130:131], s[12:13], 0, v[174:175]
	s_movk_i32 s12, 0x5000
	v_lshl_add_u64 v[128:129], s[70:71], 0, v[128:129]
	v_add_co_u32_e32 v132, vcc, s12, v130
	v_lshl_add_u64 v[176:177], v[128:129], 0, v[174:175]
	s_nop 0
	v_addc_co_u32_e32 v133, vcc, 0, v131, vcc
	global_load_dwordx4 v[140:143], v[132:133], off
	global_load_dwordx4 v[144:147], v[176:177], off offset:16 nt
	global_load_dwordx4 v[148:151], v[176:177], off nt
	s_mov_b64 s[12:13], 0x5000
	v_lshl_add_u64 v[128:129], v[130:131], 0, s[12:13]
	global_load_dwordx4 v[136:139], v[128:129], off offset:16
	global_load_dwordx4 v[132:135], v[128:129], off offset:512
	global_load_dwordx4 v[162:165], v[176:177], off offset:512 nt
	global_load_dwordx4 v[200:203], v[176:177], off offset:528 nt
	s_nop 0
	global_load_dwordx4 v[128:131], v[128:129], off offset:528
	v_readlane_b32 s69, v252, 1
	v_readlane_b32 s72, v252, 4
	v_readlane_b32 s73, v252, 5
	v_readlane_b32 s74, v252, 6
	v_readlane_b32 s75, v252, 7
	s_waitcnt vmcnt(0)
	v_pk_fma_f32 v[118:119], v[118:119], v[138:139], v[146:147]
	v_pk_fma_f32 v[114:115], v[114:115], v[142:143], v[150:151]
	v_pk_fma_f32 v[112:113], v[112:113], v[140:141], v[148:149]
	v_pk_fma_f32 v[116:117], v[116:117], v[136:137], v[144:145]
	v_pk_fma_f32 v[62:63], v[62:63], v[134:135], v[164:165]
	v_pk_fma_f32 v[60:61], v[60:61], v[132:133], v[162:163]
	v_mul_f32_e32 v144, v113, v113
	v_mul_f32_e32 v145, v115, v115
	v_mul_f32_e32 v146, v117, v117
	v_mul_f32_e32 v147, v119, v119
	v_pk_fma_f32 v[66:67], v[66:67], v[130:131], v[202:203]
	v_pk_fma_f32 v[64:65], v[64:65], v[128:129], v[200:201]
	v_mul_f32_e32 v148, v61, v61
	v_mul_f32_e32 v149, v63, v63
	v_fmac_f32_e32 v144, v112, v112
	v_fmac_f32_e32 v145, v114, v114
	v_fmac_f32_e32 v146, v116, v116
	v_fmac_f32_e32 v147, v118, v118
	v_mul_f32_e32 v150, v65, v65
	v_mul_f32_e32 v151, v67, v67
	v_fmac_f32_e32 v148, v60, v60
	v_fmac_f32_e32 v149, v62, v62
	v_add_f32_e32 v144, v144, v145
	v_add_f32_e32 v145, v146, v147
	v_fmac_f32_e32 v150, v64, v64
	v_fmac_f32_e32 v151, v66, v66
	v_add_f32_e32 v146, v148, v149
	v_add_f32_e32 v144, v144, v145
	v_add_f32_e32 v144, v144, v146
	v_add_f32_e32 v145, v150, v151
	v_add_f32_e32 v144, v144, v145
	ds_bpermute_b32 v145, v213, v144
	v_mov_b32_e32 v230, v176
	v_mov_b32_e32 v231, v177
	s_waitcnt lgkmcnt(0)
	v_add_f32_e32 v144, v144, v145
	ds_bpermute_b32 v145, v214, v144
	s_and_saveexec_b64 s[12:13], s[0:1]
	s_cbranch_execz .LBB0_1415
	s_waitcnt lgkmcnt(0)
	v_add_f32_e32 v144, v144, v145
	ds_write_b32 v188, v144
.LBB0_1415:
	s_or_b64 exec, exec, s[12:13]
	v_add_co_u32_e32 v190, vcc, 0x10000, v176
	v_lshl_add_u64 v[148:149], v[176:177], 0, s[88:89]
	s_nop 0
	v_addc_co_u32_e32 v191, vcc, 0, v177, vcc
	v_mov_b32_e32 v216, v190
	v_mov_b32_e32 v217, v191
	s_waitcnt lgkmcnt(0)
	global_load_dwordx4 v[144:147], v[190:191], off nt
	s_mov_b64 s[12:13], 0x10200
	global_load_dwordx4 v[148:151], v[148:149], off offset:16 nt
	s_nop 0
	global_load_dwordx4 v[162:165], v[190:191], off offset:512 nt
	v_lshl_add_u64 v[200:201], v[176:177], 0, s[12:13]
	global_load_dwordx4 v[200:203], v[200:201], off offset:16 nt
	s_waitcnt vmcnt(3)
	v_pk_fma_f32 v[122:123], v[122:123], v[142:143], v[146:147]
	v_pk_fma_f32 v[120:121], v[120:121], v[140:141], v[144:145]
	s_waitcnt vmcnt(2)
	v_pk_fma_f32 v[126:127], v[126:127], v[138:139], v[150:151]
	v_pk_fma_f32 v[124:125], v[124:125], v[136:137], v[148:149]
	s_waitcnt vmcnt(1)
	v_pk_fma_f32 v[78:79], v[78:79], v[134:135], v[164:165]
	v_pk_fma_f32 v[76:77], v[76:77], v[132:133], v[162:163]
	v_mul_f32_e32 v144, v121, v121
	v_mul_f32_e32 v145, v123, v123
	v_mul_f32_e32 v146, v125, v125
	v_mul_f32_e32 v147, v127, v127
	s_waitcnt vmcnt(0)
	v_pk_fma_f32 v[90:91], v[90:91], v[130:131], v[202:203]
	v_pk_fma_f32 v[88:89], v[88:89], v[128:129], v[200:201]
	v_mul_f32_e32 v148, v77, v77
	v_mul_f32_e32 v149, v79, v79
	v_fmac_f32_e32 v144, v120, v120
	v_fmac_f32_e32 v145, v122, v122
	v_fmac_f32_e32 v146, v124, v124
	v_fmac_f32_e32 v147, v126, v126
	v_mul_f32_e32 v150, v89, v89
	v_mul_f32_e32 v151, v91, v91
	v_fmac_f32_e32 v148, v76, v76
	v_fmac_f32_e32 v149, v78, v78
	v_add_f32_e32 v144, v144, v145
	v_add_f32_e32 v145, v146, v147
	v_fmac_f32_e32 v150, v88, v88
	v_fmac_f32_e32 v151, v90, v90
	v_add_f32_e32 v146, v148, v149
	v_add_f32_e32 v144, v144, v145
	v_add_f32_e32 v144, v144, v146
	v_add_f32_e32 v145, v150, v151
	v_add_f32_e32 v144, v144, v145
	ds_bpermute_b32 v145, v213, v144
	s_waitcnt lgkmcnt(0)
	v_add_f32_e32 v144, v144, v145
	ds_bpermute_b32 v145, v214, v144
	s_and_saveexec_b64 s[12:13], s[0:1]
	s_cbranch_execz .LBB0_1417
	s_waitcnt lgkmcnt(0)
	v_add_f32_e32 v144, v144, v145
	ds_write_b32 v188, v144 offset:256
; #define LAS __attribute__((address_space(3)))
; #define EF_LOAD(buf, g_) do { const float* xp_ = xi + (size_t)(((g_) >> 2) * 128 + ((g_) & 3) * 16) * DM; \
;             _Pragma("unroll") for (int bj = 0; bj < 2; ++bj) _Pragma("unroll") for (int n = 0; n < 2; ++n) xv[buf][bj][n] = *(const f32x4*)(xp_ + bj * 128 + n * 4); } while (0)
;     __device__ __forceinline__ void fused(Acc& acc, const pg8::Unit& u, int wr, int wc, int fr, int fq, LAS unsigned char* lds, int wid, int lane) const {
;     ...
;         LAS float* P = (LAS float*)lds;
;         LAS float* S = (LAS float*)(lds + 4096);
; #pragma unroll
;         for (int g_ = 0; g_ < 8; ++g_) {
;             EF_LOAD(0, g_);
;             float sq = 0.f;
; #pragma unroll
;             for (int bj = 0; bj < 2; ++bj)
; #pragma unroll
;                 for (int n = 0; n < 2; ++n) { const f32x4 xn = xv[0][bj][n] + gt[bj][n] * acc[g_ >> 2][bj][g_ & 3][n]; acc[g_ >> 2][bj][g_ & 3][n] = xn;
;                     if (MODE == 1) *(f32x4*)(xo + (size_t)((g_ >> 2) * 128 + (g_ & 3) * 16) * DM + bj * 128 + n * 4) = xn;
;                     sq += (xn[0] * xn[0] + xn[1] * xn[1]) + (xn[2] * xn[2] + xn[3] * xn[3]); }
;             sq += __shfl_xor(sq, 16); sq += __shfl_xor(sq, 32);
;             if (fq == 0) P[((g_ >> 2) * 128 + wr * 64 + (g_ & 3) * 16 + fr) * 4 + wc] = sq;
;         }
.LBB0_1417:
	s_or_b64 exec, exec, s[12:13]
	v_add_co_u32_e32 v190, vcc, 0x20000, v176
	s_mov_b64 s[12:13], 0x20000
	s_nop 0
	v_addc_co_u32_e32 v191, vcc, 0, v177, vcc
	v_mov_b32_e32 v218, v190
	v_mov_b32_e32 v219, v191
	s_waitcnt lgkmcnt(0)
	global_load_dwordx4 v[144:147], v[190:191], off nt
	v_lshl_add_u64 v[148:149], v[176:177], 0, s[12:13]
	s_mov_b64 s[12:13], 0x20200
	global_load_dwordx4 v[148:151], v[148:149], off offset:16 nt
	s_nop 0
	global_load_dwordx4 v[162:165], v[190:191], off offset:512 nt
	v_lshl_add_u64 v[200:201], v[176:177], 0, s[12:13]
	global_load_dwordx4 v[200:203], v[200:201], off offset:16 nt
	s_waitcnt vmcnt(3)
	v_pk_fma_f32 v[110:111], v[110:111], v[142:143], v[146:147]
	v_pk_fma_f32 v[108:109], v[108:109], v[140:141], v[144:145]
	s_waitcnt vmcnt(2)
	v_pk_fma_f32 v[106:107], v[106:107], v[138:139], v[150:151]
	v_pk_fma_f32 v[104:105], v[104:105], v[136:137], v[148:149]
	s_waitcnt vmcnt(1)
	v_pk_fma_f32 v[102:103], v[102:103], v[134:135], v[164:165]
	v_pk_fma_f32 v[100:101], v[100:101], v[132:133], v[162:163]
	v_mul_f32_e32 v144, v109, v109
	v_mul_f32_e32 v145, v111, v111
	v_mul_f32_e32 v146, v105, v105
	v_mul_f32_e32 v147, v107, v107
	s_waitcnt vmcnt(0)
	v_pk_fma_f32 v[98:99], v[98:99], v[130:131], v[202:203]
	v_pk_fma_f32 v[96:97], v[96:97], v[128:129], v[200:201]
	v_mul_f32_e32 v148, v101, v101
	v_mul_f32_e32 v149, v103, v103
	v_fmac_f32_e32 v144, v108, v108
	v_fmac_f32_e32 v145, v110, v110
	v_fmac_f32_e32 v146, v104, v104
	v_fmac_f32_e32 v147, v106, v106
	v_mul_f32_e32 v150, v97, v97
	v_mul_f32_e32 v151, v99, v99
	v_fmac_f32_e32 v148, v100, v100
	v_fmac_f32_e32 v149, v102, v102
	v_add_f32_e32 v144, v144, v145
	v_add_f32_e32 v145, v146, v147
	v_fmac_f32_e32 v150, v96, v96
	v_fmac_f32_e32 v151, v98, v98
	v_add_f32_e32 v146, v148, v149
	v_add_f32_e32 v144, v144, v145
	v_add_f32_e32 v144, v144, v146
	v_add_f32_e32 v145, v150, v151
	v_add_f32_e32 v144, v144, v145
	ds_bpermute_b32 v145, v213, v144
	s_waitcnt lgkmcnt(0)
	v_add_f32_e32 v144, v144, v145
	ds_bpermute_b32 v145, v214, v144
	s_and_saveexec_b64 s[12:13], s[0:1]
	s_cbranch_execz .LBB0_1419
	s_waitcnt lgkmcnt(0)
	v_add_f32_e32 v144, v144, v145
	ds_write_b32 v188, v144 offset:512
.LBB0_1419:
	s_or_b64 exec, exec, s[12:13]
	v_add_co_u32_e32 v190, vcc, 0x30000, v176
	s_mov_b64 s[12:13], 0x30000
	s_nop 0
	v_addc_co_u32_e32 v191, vcc, 0, v177, vcc
	v_mov_b32_e32 v220, v190
	v_mov_b32_e32 v221, v191
	s_waitcnt lgkmcnt(0)
	global_load_dwordx4 v[144:147], v[190:191], off nt
	v_lshl_add_u64 v[148:149], v[176:177], 0, s[12:13]
	s_mov_b64 s[12:13], 0x30200
	global_load_dwordx4 v[148:151], v[148:149], off offset:16 nt
	s_nop 0
	global_load_dwordx4 v[162:165], v[190:191], off offset:512 nt
	v_lshl_add_u64 v[200:201], v[176:177], 0, s[12:13]
	global_load_dwordx4 v[200:203], v[200:201], off offset:16 nt
	s_waitcnt vmcnt(3)
	v_pk_fma_f32 v[94:95], v[94:95], v[142:143], v[146:147]
	v_pk_fma_f32 v[92:93], v[92:93], v[140:141], v[144:145]
	s_waitcnt vmcnt(2)
	v_pk_fma_f32 v[86:87], v[86:87], v[138:139], v[150:151]
	v_pk_fma_f32 v[84:85], v[84:85], v[136:137], v[148:149]
	s_waitcnt vmcnt(1)
	v_pk_fma_f32 v[82:83], v[82:83], v[134:135], v[164:165]
	v_pk_fma_f32 v[80:81], v[80:81], v[132:133], v[162:163]
	v_mul_f32_e32 v144, v93, v93
	v_mul_f32_e32 v145, v95, v95
	v_mul_f32_e32 v146, v85, v85
	v_mul_f32_e32 v147, v87, v87
	s_waitcnt vmcnt(0)
	v_pk_fma_f32 v[74:75], v[74:75], v[130:131], v[202:203]
	v_pk_fma_f32 v[72:73], v[72:73], v[128:129], v[200:201]
	v_mul_f32_e32 v148, v81, v81
	v_mul_f32_e32 v149, v83, v83
	v_fmac_f32_e32 v144, v92, v92
	v_fmac_f32_e32 v145, v94, v94
	v_fmac_f32_e32 v146, v84, v84
	v_fmac_f32_e32 v147, v86, v86
	v_mul_f32_e32 v150, v73, v73
	v_mul_f32_e32 v151, v75, v75
	v_fmac_f32_e32 v148, v80, v80
	v_fmac_f32_e32 v149, v82, v82
	v_add_f32_e32 v144, v144, v145
	v_add_f32_e32 v145, v146, v147
	v_fmac_f32_e32 v150, v72, v72
	v_fmac_f32_e32 v151, v74, v74
	v_add_f32_e32 v146, v148, v149
	v_add_f32_e32 v144, v144, v145
	v_add_f32_e32 v144, v144, v146
	v_add_f32_e32 v145, v150, v151
	v_add_f32_e32 v144, v144, v145
	ds_bpermute_b32 v145, v213, v144
	s_waitcnt lgkmcnt(0)
	v_add_f32_e32 v144, v144, v145
	ds_bpermute_b32 v145, v214, v144
	s_and_saveexec_b64 s[12:13], s[0:1]
	s_cbranch_execz .LBB0_1421
	s_waitcnt lgkmcnt(0)
	v_add_f32_e32 v144, v144, v145
	ds_write_b32 v188, v144 offset:768
.LBB0_1421:
	s_or_b64 exec, exec, s[12:13]
	v_add_co_u32_e32 v190, vcc, 0x80000, v176
	s_mov_b64 s[12:13], 0x80000
	s_nop 0
	v_addc_co_u32_e32 v191, vcc, 0, v177, vcc
	v_mov_b32_e32 v222, v190
	v_mov_b32_e32 v223, v191
	s_waitcnt lgkmcnt(0)
	global_load_dwordx4 v[144:147], v[190:191], off nt
	v_lshl_add_u64 v[148:149], v[176:177], 0, s[12:13]
	s_mov_b64 s[12:13], 0x80200
	global_load_dwordx4 v[148:151], v[148:149], off offset:16 nt
	s_nop 0
	global_load_dwordx4 v[162:165], v[190:191], off offset:512 nt
	v_lshl_add_u64 v[200:201], v[176:177], 0, s[12:13]
	global_load_dwordx4 v[200:203], v[200:201], off offset:16 nt
	s_waitcnt vmcnt(3)
	v_pk_fma_f32 v[70:71], v[70:71], v[142:143], v[146:147]
	v_pk_fma_f32 v[68:69], v[68:69], v[140:141], v[144:145]
	s_waitcnt vmcnt(2)
	v_pk_fma_f32 v[58:59], v[58:59], v[138:139], v[150:151]
	v_pk_fma_f32 v[56:57], v[56:57], v[136:137], v[148:149]
	s_waitcnt vmcnt(1)
	v_pk_fma_f32 v[54:55], v[54:55], v[134:135], v[164:165]
	v_pk_fma_f32 v[52:53], v[52:53], v[132:133], v[162:163]
	v_mul_f32_e32 v144, v69, v69
	v_mul_f32_e32 v145, v71, v71
	v_mul_f32_e32 v146, v57, v57
	v_mul_f32_e32 v147, v59, v59
	s_waitcnt vmcnt(0)
	v_pk_fma_f32 v[50:51], v[50:51], v[130:131], v[202:203]
	v_pk_fma_f32 v[48:49], v[48:49], v[128:129], v[200:201]
	v_mul_f32_e32 v148, v53, v53
	v_mul_f32_e32 v149, v55, v55
	v_fmac_f32_e32 v144, v68, v68
	v_fmac_f32_e32 v145, v70, v70
	v_fmac_f32_e32 v146, v56, v56
	v_fmac_f32_e32 v147, v58, v58
	v_mul_f32_e32 v150, v49, v49
	v_mul_f32_e32 v151, v51, v51
	v_fmac_f32_e32 v148, v52, v52
	v_fmac_f32_e32 v149, v54, v54
	v_add_f32_e32 v144, v144, v145
	v_add_f32_e32 v145, v146, v147
	v_fmac_f32_e32 v150, v48, v48
	v_fmac_f32_e32 v151, v50, v50
	v_add_f32_e32 v146, v148, v149
	v_add_f32_e32 v144, v144, v145
	v_add_f32_e32 v144, v144, v146
	v_add_f32_e32 v145, v150, v151
	v_add_f32_e32 v144, v144, v145
	ds_bpermute_b32 v145, v213, v144
	s_waitcnt lgkmcnt(0)
	v_add_f32_e32 v144, v144, v145
	ds_bpermute_b32 v145, v214, v144
	s_and_saveexec_b64 s[12:13], s[0:1]
	s_cbranch_execz .LBB0_1423
	s_waitcnt lgkmcnt(0)
	v_add_f32_e32 v144, v144, v145
	ds_write_b32 v183, v144
; #define LAS __attribute__((address_space(3)))
; #define EF_LOAD(buf, g_) do { const float* xp_ = xi + (size_t)(((g_) >> 2) * 128 + ((g_) & 3) * 16) * DM; \
;             _Pragma("unroll") for (int bj = 0; bj < 2; ++bj) _Pragma("unroll") for (int n = 0; n < 2; ++n) xv[buf][bj][n] = *(const f32x4*)(xp_ + bj * 128 + n * 4); } while (0)
;     __device__ __forceinline__ void fused(Acc& acc, const pg8::Unit& u, int wr, int wc, int fr, int fq, LAS unsigned char* lds, int wid, int lane) const {
;     ...
;         LAS float* P = (LAS float*)lds;
;         LAS float* S = (LAS float*)(lds + 4096);
; #pragma unroll
;         for (int g_ = 0; g_ < 8; ++g_) {
;             EF_LOAD(0, g_);
;             float sq = 0.f;
; #pragma unroll
;             for (int bj = 0; bj < 2; ++bj)
; #pragma unroll
;                 for (int n = 0; n < 2; ++n) { const f32x4 xn = xv[0][bj][n] + gt[bj][n] * acc[g_ >> 2][bj][g_ & 3][n]; acc[g_ >> 2][bj][g_ & 3][n] = xn;
;                     if (MODE == 1) *(f32x4*)(xo + (size_t)((g_ >> 2) * 128 + (g_ & 3) * 16) * DM + bj * 128 + n * 4) = xn;
;                     sq += (xn[0] * xn[0] + xn[1] * xn[1]) + (xn[2] * xn[2] + xn[3] * xn[3]); }
;             sq += __shfl_xor(sq, 16); sq += __shfl_xor(sq, 32);
;             if (fq == 0) P[((g_ >> 2) * 128 + wr * 64 + (g_ & 3) * 16 + fr) * 4 + wc] = sq;
;         }
.LBB0_1423:
	s_or_b64 exec, exec, s[12:13]
	v_add_co_u32_e32 v190, vcc, 0x90000, v176
	s_mov_b64 s[12:13], 0x90000
	s_nop 0
	v_addc_co_u32_e32 v191, vcc, 0, v177, vcc
	v_mov_b32_e32 v224, v190
	v_mov_b32_e32 v225, v191
	s_waitcnt lgkmcnt(0)
	global_load_dwordx4 v[144:147], v[190:191], off nt
	v_lshl_add_u64 v[148:149], v[176:177], 0, s[12:13]
	s_mov_b64 s[12:13], 0x90200
	global_load_dwordx4 v[148:151], v[148:149], off offset:16 nt
	s_nop 0
	global_load_dwordx4 v[162:165], v[190:191], off offset:512 nt
	v_lshl_add_u64 v[200:201], v[176:177], 0, s[12:13]
	global_load_dwordx4 v[200:203], v[200:201], off offset:16 nt
	s_waitcnt vmcnt(3)
	v_pk_fma_f32 v[46:47], v[46:47], v[142:143], v[146:147]
	v_pk_fma_f32 v[44:45], v[44:45], v[140:141], v[144:145]
	s_waitcnt vmcnt(2)
	v_pk_fma_f32 v[42:43], v[42:43], v[138:139], v[150:151]
	v_pk_fma_f32 v[40:41], v[40:41], v[136:137], v[148:149]
	s_waitcnt vmcnt(1)
	v_pk_fma_f32 v[38:39], v[38:39], v[134:135], v[164:165]
	v_pk_fma_f32 v[36:37], v[36:37], v[132:133], v[162:163]
	v_mul_f32_e32 v144, v45, v45
	v_mul_f32_e32 v145, v47, v47
	v_mul_f32_e32 v146, v41, v41
	v_mul_f32_e32 v147, v43, v43
	s_waitcnt vmcnt(0)
	v_pk_fma_f32 v[34:35], v[34:35], v[130:131], v[202:203]
	v_pk_fma_f32 v[32:33], v[32:33], v[128:129], v[200:201]
	v_mul_f32_e32 v148, v37, v37
	v_mul_f32_e32 v149, v39, v39
	v_fmac_f32_e32 v144, v44, v44
	v_fmac_f32_e32 v145, v46, v46
	v_fmac_f32_e32 v146, v40, v40
	v_fmac_f32_e32 v147, v42, v42
	v_mul_f32_e32 v150, v33, v33
	v_mul_f32_e32 v151, v35, v35
	v_fmac_f32_e32 v148, v36, v36
	v_fmac_f32_e32 v149, v38, v38
	v_add_f32_e32 v144, v144, v145
	v_add_f32_e32 v145, v146, v147
	v_fmac_f32_e32 v150, v32, v32
	v_fmac_f32_e32 v151, v34, v34
	v_add_f32_e32 v146, v148, v149
	v_add_f32_e32 v144, v144, v145
	v_add_f32_e32 v144, v144, v146
	v_add_f32_e32 v145, v150, v151
	v_add_f32_e32 v144, v144, v145
	ds_bpermute_b32 v145, v213, v144
	s_waitcnt lgkmcnt(0)
	v_add_f32_e32 v144, v144, v145
	ds_bpermute_b32 v145, v214, v144
	s_and_saveexec_b64 s[12:13], s[0:1]
	s_cbranch_execz .LBB0_1425
	s_waitcnt lgkmcnt(0)
	v_add_f32_e32 v144, v144, v145
	ds_write_b32 v184, v144
.LBB0_1425:
	s_or_b64 exec, exec, s[12:13]
	v_add_co_u32_e32 v190, vcc, 0xa0000, v176
	s_mov_b64 s[12:13], 0xa0000
	s_nop 0
	v_addc_co_u32_e32 v191, vcc, 0, v177, vcc
	v_mov_b32_e32 v226, v190
	v_mov_b32_e32 v227, v191
	v_lshl_add_u64 v[148:149], v[176:177], 0, s[12:13]
	s_mov_b64 s[12:13], 0xa0200
	s_waitcnt lgkmcnt(0)
	global_load_dwordx4 v[144:147], v[190:191], off nt
	v_lshl_add_u64 v[200:201], v[176:177], 0, s[12:13]
	global_load_dwordx4 v[148:151], v[148:149], off offset:16 nt
	s_nop 0
	global_load_dwordx4 v[162:165], v[190:191], off offset:512 nt
	s_waitcnt vmcnt(2)
	v_pk_fma_f32 v[146:147], v[30:31], v[142:143], v[146:147]
	global_load_dwordx4 v[200:203], v[200:201], off offset:16 nt
	v_pk_fma_f32 v[144:145], v[28:29], v[140:141], v[144:145]
	s_waitcnt vmcnt(2)
	v_pk_fma_f32 v[150:151], v[26:27], v[138:139], v[150:151]
	v_pk_fma_f32 v[148:149], v[24:25], v[136:137], v[148:149]
	s_waitcnt vmcnt(1)
	v_pk_fma_f32 v[26:27], v[22:23], v[134:135], v[164:165]
	v_pk_fma_f32 v[24:25], v[20:21], v[132:133], v[162:163]
	v_mul_f32_e32 v21, v27, v27
	v_mul_f32_e32 v20, v25, v25
	v_fmac_f32_e32 v20, v24, v24
	v_fmac_f32_e32 v21, v26, v26
	s_waitcnt vmcnt(0)
	v_pk_fma_f32 v[30:31], v[18:19], v[130:131], v[202:203]
	v_pk_fma_f32 v[28:29], v[16:17], v[128:129], v[200:201]
	v_mul_f32_e32 v16, v145, v145
	v_mul_f32_e32 v17, v147, v147
	v_mul_f32_e32 v18, v149, v149
	v_mul_f32_e32 v19, v151, v151
	v_fmac_f32_e32 v16, v144, v144
	v_fmac_f32_e32 v17, v146, v146
	v_fmac_f32_e32 v18, v148, v148
	v_fmac_f32_e32 v19, v150, v150
	v_mul_f32_e32 v22, v29, v29
	v_mul_f32_e32 v23, v31, v31
	v_add_f32_e32 v16, v16, v17
	v_add_f32_e32 v17, v18, v19
	v_fmac_f32_e32 v22, v28, v28
	v_fmac_f32_e32 v23, v30, v30
	v_add_f32_e32 v18, v20, v21
	v_add_f32_e32 v16, v16, v17
	v_add_f32_e32 v16, v16, v18
	v_add_f32_e32 v17, v22, v23
	v_add_f32_e32 v16, v16, v17
	ds_bpermute_b32 v17, v213, v16
	s_waitcnt lgkmcnt(0)
	v_add_f32_e32 v16, v16, v17
	ds_bpermute_b32 v17, v214, v16
	s_and_saveexec_b64 s[12:13], s[0:1]
	s_cbranch_execz .LBB0_1427
	s_waitcnt lgkmcnt(0)
	v_add_f32_e32 v16, v16, v17
	ds_write_b32 v185, v16
; #define LAS __attribute__((address_space(3)))
; #define EF_LOAD(buf, g_) do { const float* xp_ = xi + (size_t)(((g_) >> 2) * 128 + ((g_) & 3) * 16) * DM; \
;             _Pragma("unroll") for (int bj = 0; bj < 2; ++bj) _Pragma("unroll") for (int n = 0; n < 2; ++n) xv[buf][bj][n] = *(const f32x4*)(xp_ + bj * 128 + n * 4); } while (0)
;     __device__ __forceinline__ void fused(Acc& acc, const pg8::Unit& u, int wr, int wc, int fr, int fq, LAS unsigned char* lds, int wid, int lane) const {
;     ...
;         LAS float* P = (LAS float*)lds;
;         LAS float* S = (LAS float*)(lds + 4096);
; #pragma unroll
;         for (int g_ = 0; g_ < 8; ++g_) {
;             EF_LOAD(0, g_);
;             float sq = 0.f;
; #pragma unroll
;             for (int bj = 0; bj < 2; ++bj)
; #pragma unroll
;                 for (int n = 0; n < 2; ++n) { const f32x4 xn = xv[0][bj][n] + gt[bj][n] * acc[g_ >> 2][bj][g_ & 3][n]; acc[g_ >> 2][bj][g_ & 3][n] = xn;
;                     if (MODE == 1) *(f32x4*)(xo + (size_t)((g_ >> 2) * 128 + (g_ & 3) * 16) * DM + bj * 128 + n * 4) = xn;
;                     sq += (xn[0] * xn[0] + xn[1] * xn[1]) + (xn[2] * xn[2] + xn[3] * xn[3]); }
;             sq += __shfl_xor(sq, 16); sq += __shfl_xor(sq, 32);
;             if (fq == 0) P[((g_ >> 2) * 128 + wr * 64 + (g_ & 3) * 16 + fr) * 4 + wc] = sq;
;         }
.LBB0_1427:
	s_or_b64 exec, exec, s[12:13]
	v_add_co_u32_e32 v190, vcc, 0xb0000, v176
	s_mov_b64 s[12:13], 0xb0000
	s_nop 0
	v_addc_co_u32_e32 v191, vcc, 0, v177, vcc
	s_waitcnt lgkmcnt(0)
	global_load_dwordx4 v[16:19], v[190:191], off nt
	v_lshl_add_u64 v[20:21], v[176:177], 0, s[12:13]
	s_mov_b64 s[12:13], 0xb0200
	global_load_dwordx4 v[20:23], v[20:21], off offset:16 nt
	s_nop 0
	global_load_dwordx4 v[162:165], v[190:191], off offset:512 nt
	v_lshl_add_u64 v[176:177], v[176:177], 0, s[12:13]
	global_load_dwordx4 v[200:203], v[176:177], off offset:16 nt
	s_waitcnt vmcnt(3)
	v_pk_fma_f32 v[14:15], v[14:15], v[142:143], v[18:19]
	v_pk_fma_f32 v[12:13], v[12:13], v[140:141], v[16:17]
	s_waitcnt vmcnt(2)
	v_pk_fma_f32 v[10:11], v[10:11], v[138:139], v[22:23]
	v_pk_fma_f32 v[8:9], v[8:9], v[136:137], v[20:21]
	s_waitcnt vmcnt(1)
	v_pk_fma_f32 v[2:3], v[2:3], v[134:135], v[164:165]
	v_pk_fma_f32 v[0:1], v[0:1], v[132:133], v[162:163]
	v_mul_f32_e32 v16, v13, v13
	v_mul_f32_e32 v17, v15, v15
	v_mul_f32_e32 v18, v9, v9
	v_mul_f32_e32 v19, v11, v11
	s_waitcnt vmcnt(0)
	v_pk_fma_f32 v[6:7], v[6:7], v[130:131], v[202:203]
	v_pk_fma_f32 v[4:5], v[4:5], v[128:129], v[200:201]
	v_mul_f32_e32 v20, v1, v1
	v_mul_f32_e32 v21, v3, v3
	v_fmac_f32_e32 v16, v12, v12
	v_fmac_f32_e32 v17, v14, v14
	v_fmac_f32_e32 v18, v8, v8
	v_fmac_f32_e32 v19, v10, v10
	v_mul_f32_e32 v22, v5, v5
	v_mul_f32_e32 v23, v7, v7
	v_fmac_f32_e32 v20, v0, v0
	v_fmac_f32_e32 v21, v2, v2
	v_add_f32_e32 v16, v16, v17
	v_add_f32_e32 v17, v18, v19
	v_fmac_f32_e32 v22, v4, v4
	v_fmac_f32_e32 v23, v6, v6
	v_add_f32_e32 v18, v20, v21
	v_add_f32_e32 v16, v16, v17
	v_add_f32_e32 v16, v16, v18
	v_add_f32_e32 v17, v22, v23
	v_add_f32_e32 v16, v16, v17
	ds_bpermute_b32 v17, v213, v16
	global_store_dwordx4 v[230:231], v[112:115], off
	global_store_dwordx4 v[230:231], v[116:119], off offset:16
	global_store_dwordx4 v[230:231], v[60:63], off offset:512
	global_store_dwordx4 v[230:231], v[64:67], off offset:528
	global_store_dwordx4 v[216:217], v[120:123], off
	global_store_dwordx4 v[216:217], v[124:127], off offset:16
	global_store_dwordx4 v[216:217], v[76:79], off offset:512
	global_store_dwordx4 v[216:217], v[88:91], off offset:528
	global_store_dwordx4 v[218:219], v[108:111], off
	global_store_dwordx4 v[218:219], v[104:107], off offset:16
	global_store_dwordx4 v[218:219], v[100:103], off offset:512
	global_store_dwordx4 v[218:219], v[96:99], off offset:528
	global_store_dwordx4 v[220:221], v[92:95], off
	global_store_dwordx4 v[220:221], v[84:87], off offset:16
	global_store_dwordx4 v[220:221], v[80:83], off offset:512
	global_store_dwordx4 v[220:221], v[72:75], off offset:528
	global_store_dwordx4 v[222:223], v[68:71], off
	global_store_dwordx4 v[222:223], v[56:59], off offset:16
	global_store_dwordx4 v[222:223], v[52:55], off offset:512
	global_store_dwordx4 v[222:223], v[48:51], off offset:528
	global_store_dwordx4 v[224:225], v[44:47], off
	global_store_dwordx4 v[224:225], v[40:43], off offset:16
	global_store_dwordx4 v[224:225], v[36:39], off offset:512
	global_store_dwordx4 v[224:225], v[32:35], off offset:528
	global_store_dwordx4 v[226:227], v[144:147], off
	global_store_dwordx4 v[226:227], v[148:151], off offset:16
	global_store_dwordx4 v[226:227], v[24:27], off offset:512
	global_store_dwordx4 v[226:227], v[28:31], off offset:528
	global_store_dwordx4 v[190:191], v[12:15], off
	global_store_dwordx4 v[190:191], v[8:11], off offset:16
	global_store_dwordx4 v[190:191], v[0:3], off offset:512
	global_store_dwordx4 v[190:191], v[4:7], off offset:528
	s_waitcnt lgkmcnt(0)
	v_add_f32_e32 v16, v16, v17
	ds_bpermute_b32 v17, v214, v16
	s_and_saveexec_b64 s[12:13], s[0:1]
	s_cbranch_execz .LBB0_1429
	s_waitcnt lgkmcnt(0)
	v_add_f32_e32 v16, v16, v17
	ds_write_b32 v186, v16
